# best variant (no setprio, merged waits) + each accumulator's k=0/k=1 MFMAs issued back-to-back in GEMM K-loops
# speedup vs baseline: 1.0101x; 1.0057x over previous
; #define PG8_STAGE(bufoff, gbase, voff) do { _Pragma("unroll") for (int _i = 0; _i < 2; ++_i) \
;         __builtin_amdgcn_global_load_lds((const unsigned*)((const char*)(gbase) + (voff)[_i]), (PG8_LAS unsigned*)(lds + (bufoff) + ldsw + _i * 8192), 16, 0, 0); } while (0)
; #define PG8_LDA(dst, b, h) do { _Pragma("unroll") for (int m = 0; m < 4; ++m) _Pragma("unroll") for (int k = 0; k < 2; ++k) dst[m][k] = *(const PG8_LAS bf16x8*)(lds + PG8_SA(b, h) + aoff + m * 2048 + k * 1024); } while (0)
; #define PG8_LDB(dst, b, h) do { _Pragma("unroll") for (int n = 0; n < 2; ++n) _Pragma("unroll") for (int k = 0; k < 2; ++k) dst[n][k] = *(const PG8_LAS bf16x8*)(lds + PG8_SB(b, h) + boff + n * 2048 + k * 1024); } while (0)
; #define PG8_MMA(ai, bj, At, Bt) do { __builtin_amdgcn_s_setprio(1); _Pragma("unroll") for (int m = 0; m < 4; ++m) _Pragma("unroll") for (int n = 0; n < 2; ++n) _Pragma("unroll") for (int k = 0; k < 2; ++k) \
;         acc[ai][bj][m][n] = __builtin_amdgcn_mfma_f32_16x16x32_bf16(Bt[n][k], At[m][k], acc[ai][bj][m][n], 0, 0, 0); __builtin_amdgcn_s_setprio(0); } while (0)
; #define PG8_WAIT_V(n) asm volatile("s_waitcnt vmcnt(" #n ")" ::: "memory")
; #define PG8_WAIT_L(n) asm volatile("s_waitcnt lgkmcnt(" #n ")" ::: "memory")
; #define PG8_BAR __builtin_amdgcn_s_barrier()
; #define PG8_SCHED __builtin_amdgcn_sched_barrier(0)
; template <class Epi, class Sched, bool ALIGN_EPI = false, bool SP2 = false>
; __device__ __forceinline__ void gemm_phase(PG8_LAS unsigned char* lds, const Gemm g, const Sched& S, const Epi& E) {
;     ...
;             PG8_LDB(B0, 0, 0); PG8_LDB(B1, 0, 1); PG8_SCHED; PG8_LDA(At, 0, 0); PG8_STAGE(PG8_SA(1, 1), a1 + hstep, voffA);
;             PG8_WAIT_V(8); PG8_WAIT_L(0); PG8_BAR; PG8_MMA(0, 0, At, B0); PG8_MMA(0, 1, At, B1); PG8_BAR; PG8_SCHED;
;             PG8_LDA(At, 0, 1); PG8_STAGE(PG8_SB(0, 0), b2, voffB); PG8_STAGE(PG8_SB(0, 1), b2 + hstep, voffB); PG8_STAGE(PG8_SA(0, 0), a2, voffA);
;             PG8_WAIT_V(8); PG8_WAIT_L(0); PG8_BAR; PG8_MMA(1, 0, At, B0); PG8_MMA(1, 1, At, B1); PG8_BAR; PG8_SCHED;
.LBB0_265:
	s_add_u32 s10, s16, 0xfff80080
	s_addc_u32 s11, s17, -1
	s_add_i32 s27, 0, 0x10000
	s_cmp_eq_u32 s23, 28
	s_cselect_b32 s51, s5, s11
	s_cselect_b32 s50, s7, s10
	s_cselect_b32 s19, s8, s22
	s_cselect_b32 s18, s9, s15
	s_add_i32 s10, 0, 0x14000
	v_add_u32_e32 v168, s27, v157
	v_add_u32_e32 v184, s10, v157
	ds_read_b128 v[152:155], v168
	ds_read_b128 v[160:163], v168 offset:1024
	ds_read_b128 v[164:167], v168 offset:2048
	ds_read_b128 v[168:171], v168 offset:3072
	ds_read_b128 v[172:175], v184
	ds_read_b128 v[176:179], v184 offset:1024
	ds_read_b128 v[180:183], v184 offset:2048
	ds_read_b128 v[184:187], v184 offset:3072
	v_lshl_add_u64 v[200:201], s[16:17], 0, v[148:149]
	s_add_i32 m0, s57, 0xc000
	ds_read_b128 v[188:191], v159
	ds_read_b128 v[192:195], v159 offset:1024
	ds_read_b128 v[196:199], v159 offset:2048
	ds_read_b128 v[216:219], v159 offset:3072
	ds_read_b128 v[220:223], v159 offset:4096
	ds_read_b128 v[224:227], v159 offset:5120
	ds_read_b128 v[228:231], v159 offset:6144
	ds_read_b128 v[232:235], v159 offset:7168
	global_load_lds_dwordx4 v[200:201], off
	v_lshl_add_u64 v[200:201], s[16:17], 0, v[150:151]
	s_add_i32 m0, s57, 0xe000
	s_nop 0
	global_load_lds_dwordx4 v[200:201], off
	s_waitcnt vmcnt(8) lgkmcnt(0)
	s_barrier
	v_mfma_f32_16x16x32_bf16 v[126:129], v[152:155], v[188:191], v[126:129]
	v_mfma_f32_16x16x32_bf16 v[126:129], v[160:163], v[192:195], v[126:129]
	v_mfma_f32_16x16x32_bf16 v[122:125], v[164:167], v[188:191], v[122:125]
	v_mfma_f32_16x16x32_bf16 v[122:125], v[168:171], v[192:195], v[122:125]
	v_mfma_f32_16x16x32_bf16 v[110:113], v[152:155], v[196:199], v[110:113]
	v_mfma_f32_16x16x32_bf16 v[110:113], v[160:163], v[216:219], v[110:113]
	v_mfma_f32_16x16x32_bf16 v[106:109], v[164:167], v[196:199], v[106:109]
	v_mfma_f32_16x16x32_bf16 v[106:109], v[168:171], v[216:219], v[106:109]
	v_mfma_f32_16x16x32_bf16 v[94:97], v[152:155], v[220:223], v[94:97]
	v_mfma_f32_16x16x32_bf16 v[94:97], v[160:163], v[224:227], v[94:97]
	v_mfma_f32_16x16x32_bf16 v[90:93], v[164:167], v[220:223], v[90:93]
	v_mfma_f32_16x16x32_bf16 v[90:93], v[168:171], v[224:227], v[90:93]
	v_mfma_f32_16x16x32_bf16 v[78:81], v[152:155], v[228:231], v[78:81]
	v_mfma_f32_16x16x32_bf16 v[78:81], v[160:163], v[232:235], v[78:81]
	v_mfma_f32_16x16x32_bf16 v[74:77], v[164:167], v[228:231], v[74:77]
	v_mfma_f32_16x16x32_bf16 v[74:77], v[168:171], v[232:235], v[74:77]
	v_mfma_f32_16x16x32_bf16 v[118:121], v[172:175], v[188:191], v[118:121]
	v_mfma_f32_16x16x32_bf16 v[118:121], v[176:179], v[192:195], v[118:121]
	v_mfma_f32_16x16x32_bf16 v[114:117], v[180:183], v[188:191], v[114:117]
	v_mfma_f32_16x16x32_bf16 v[114:117], v[184:187], v[192:195], v[114:117]
	v_mfma_f32_16x16x32_bf16 v[102:105], v[172:175], v[196:199], v[102:105]
	v_mfma_f32_16x16x32_bf16 v[102:105], v[176:179], v[216:219], v[102:105]
	v_mfma_f32_16x16x32_bf16 v[98:101], v[180:183], v[196:199], v[98:101]
	v_mfma_f32_16x16x32_bf16 v[98:101], v[184:187], v[216:219], v[98:101]
	v_mfma_f32_16x16x32_bf16 v[86:89], v[172:175], v[220:223], v[86:89]
	v_mfma_f32_16x16x32_bf16 v[86:89], v[176:179], v[224:227], v[86:89]
	v_mfma_f32_16x16x32_bf16 v[82:85], v[180:183], v[220:223], v[82:85]
	v_mfma_f32_16x16x32_bf16 v[82:85], v[184:187], v[224:227], v[82:85]
	v_mfma_f32_16x16x32_bf16 v[70:73], v[172:175], v[228:231], v[70:73]
	v_mfma_f32_16x16x32_bf16 v[70:73], v[176:179], v[232:235], v[70:73]
	v_mfma_f32_16x16x32_bf16 v[66:69], v[180:183], v[228:231], v[66:69]
	v_mfma_f32_16x16x32_bf16 v[66:69], v[184:187], v[232:235], v[66:69]
	s_barrier
	s_add_i32 s11, s27, s56
	v_lshl_add_u64 v[200:201], s[18:19], 0, v[0:1]
	s_mov_b32 m0, s11
	ds_read_b128 v[188:191], v159 offset:16384
	ds_read_b128 v[192:195], v159 offset:17408
	ds_read_b128 v[196:199], v159 offset:18432
	ds_read_b128 v[216:219], v159 offset:19456
	ds_read_b128 v[220:223], v159 offset:20480
	ds_read_b128 v[224:227], v159 offset:21504
	ds_read_b128 v[228:231], v159 offset:22528
	ds_read_b128 v[232:235], v159 offset:23552
	global_load_lds_dwordx4 v[200:201], off
	s_add_i32 m0, s11, 0x2000
	s_add_u32 s38, s18, 0x80000
	v_lshl_add_u64 v[236:237], s[18:19], 0, v[142:143]
	s_addc_u32 s39, s19, 0
	s_add_i32 s10, s10, s56
	global_load_lds_dwordx4 v[236:237], off
	v_lshl_add_u64 v[238:239], s[38:39], 0, v[0:1]
	s_mov_b32 m0, s10
	v_lshl_add_u64 v[240:241], s[50:51], 0, v[144:145]
	global_load_lds_dwordx4 v[238:239], off
	v_lshl_add_u64 v[238:239], s[38:39], 0, v[142:143]
	s_add_i32 m0, s10, 0x2000
	s_nop 0
	global_load_lds_dwordx4 v[238:239], off
	v_lshl_add_u64 v[238:239], s[50:51], 0, v[146:147]
	s_mov_b32 m0, s57
	s_nop 0
	global_load_lds_dwordx4 v[238:239], off
	s_mov_b32 m0, s58
	s_nop 0
	global_load_lds_dwordx4 v[240:241], off
	s_waitcnt vmcnt(8) lgkmcnt(0)
	s_barrier
; #define PG8_STAGE(bufoff, gbase, voff) do { _Pragma("unroll") for (int _i = 0; _i < 2; ++_i) \
;         __builtin_amdgcn_global_load_lds((const unsigned*)((const char*)(gbase) + (voff)[_i]), (PG8_LAS unsigned*)(lds + (bufoff) + ldsw + _i * 8192), 16, 0, 0); } while (0)
; #define PG8_LDA(dst, b, h) do { _Pragma("unroll") for (int m = 0; m < 4; ++m) _Pragma("unroll") for (int k = 0; k < 2; ++k) dst[m][k] = *(const PG8_LAS bf16x8*)(lds + PG8_SA(b, h) + aoff + m * 2048 + k * 1024); } while (0)
; #define PG8_LDB(dst, b, h) do { _Pragma("unroll") for (int n = 0; n < 2; ++n) _Pragma("unroll") for (int k = 0; k < 2; ++k) dst[n][k] = *(const PG8_LAS bf16x8*)(lds + PG8_SB(b, h) + boff + n * 2048 + k * 1024); } while (0)
; #define PG8_MMA(ai, bj, At, Bt) do { __builtin_amdgcn_s_setprio(1); _Pragma("unroll") for (int m = 0; m < 4; ++m) _Pragma("unroll") for (int n = 0; n < 2; ++n) _Pragma("unroll") for (int k = 0; k < 2; ++k) \
;         acc[ai][bj][m][n] = __builtin_amdgcn_mfma_f32_16x16x32_bf16(Bt[n][k], At[m][k], acc[ai][bj][m][n], 0, 0, 0); __builtin_amdgcn_s_setprio(0); } while (0)
; #define PG8_WAIT_V(n) asm volatile("s_waitcnt vmcnt(" #n ")" ::: "memory")
; #define PG8_WAIT_L(n) asm volatile("s_waitcnt lgkmcnt(" #n ")" ::: "memory")
; #define PG8_BAR __builtin_amdgcn_s_barrier()
; #define PG8_SCHED __builtin_amdgcn_sched_barrier(0)
; template <class Epi, class Sched, bool ALIGN_EPI = false, bool SP2 = false>
; __device__ __forceinline__ void gemm_phase(PG8_LAS unsigned char* lds, const Gemm g, const Sched& S, const Epi& E) {
;     ...
;             PG8_WAIT_V(8); PG8_WAIT_L(0); PG8_BAR; PG8_MMA(1, 0, At, B0); PG8_MMA(1, 1, At, B1); PG8_BAR; PG8_SCHED;
;             PG8_LDB(B0, 1, 0); PG8_LDB(B1, 1, 1); PG8_SCHED; PG8_LDA(At, 1, 0); PG8_STAGE(PG8_SA(0, 1), a2 + hstep, voffA);
;             PG8_WAIT_V(8); PG8_WAIT_L(0); PG8_BAR; PG8_MMA(0, 0, At, B0); PG8_MMA(0, 1, At, B1); PG8_BAR; PG8_SCHED;
;             PG8_LDA(At, 1, 1); PG8_STAGE(PG8_SB(1, 0), b3, voffB); PG8_STAGE(PG8_SB(1, 1), b3 + hstep, voffB); PG8_STAGE(PG8_SA(1, 0), a3, voffA);
;             PG8_WAIT_V(8); PG8_WAIT_L(0); PG8_BAR; PG8_MMA(1, 0, At, B0); PG8_MMA(1, 1, At, B1); PG8_BAR; PG8_SCHED;
	v_mfma_f32_16x16x32_bf16 v[62:65], v[152:155], v[188:191], v[62:65]
	v_mfma_f32_16x16x32_bf16 v[62:65], v[160:163], v[192:195], v[62:65]
	v_mfma_f32_16x16x32_bf16 v[58:61], v[164:167], v[188:191], v[58:61]
	v_mfma_f32_16x16x32_bf16 v[58:61], v[168:171], v[192:195], v[58:61]
	v_mfma_f32_16x16x32_bf16 v[50:53], v[152:155], v[196:199], v[50:53]
	v_mfma_f32_16x16x32_bf16 v[50:53], v[160:163], v[216:219], v[50:53]
	v_mfma_f32_16x16x32_bf16 v[42:45], v[164:167], v[196:199], v[42:45]
	v_mfma_f32_16x16x32_bf16 v[42:45], v[168:171], v[216:219], v[42:45]
	v_mfma_f32_16x16x32_bf16 v[34:37], v[152:155], v[220:223], v[34:37]
	v_mfma_f32_16x16x32_bf16 v[34:37], v[160:163], v[224:227], v[34:37]
	v_mfma_f32_16x16x32_bf16 v[26:29], v[164:167], v[220:223], v[26:29]
	v_mfma_f32_16x16x32_bf16 v[26:29], v[168:171], v[224:227], v[26:29]
	v_mfma_f32_16x16x32_bf16 v[18:21], v[152:155], v[228:231], v[18:21]
	v_mfma_f32_16x16x32_bf16 v[18:21], v[160:163], v[232:235], v[18:21]
	v_mfma_f32_16x16x32_bf16 v[10:13], v[164:167], v[228:231], v[10:13]
	v_mfma_f32_16x16x32_bf16 v[10:13], v[168:171], v[232:235], v[10:13]
	v_mfma_f32_16x16x32_bf16 v[54:57], v[172:175], v[188:191], v[54:57]
	v_mfma_f32_16x16x32_bf16 v[54:57], v[176:179], v[192:195], v[54:57]
	v_mfma_f32_16x16x32_bf16 v[46:49], v[180:183], v[188:191], v[46:49]
	v_mfma_f32_16x16x32_bf16 v[46:49], v[184:187], v[192:195], v[46:49]
	v_mfma_f32_16x16x32_bf16 v[38:41], v[172:175], v[196:199], v[38:41]
	v_mfma_f32_16x16x32_bf16 v[38:41], v[176:179], v[216:219], v[38:41]
	v_mfma_f32_16x16x32_bf16 v[30:33], v[180:183], v[196:199], v[30:33]
	v_mfma_f32_16x16x32_bf16 v[30:33], v[184:187], v[216:219], v[30:33]
	v_mfma_f32_16x16x32_bf16 v[22:25], v[172:175], v[220:223], v[22:25]
	v_mfma_f32_16x16x32_bf16 v[22:25], v[176:179], v[224:227], v[22:25]
	v_mfma_f32_16x16x32_bf16 v[14:17], v[180:183], v[220:223], v[14:17]
	v_mfma_f32_16x16x32_bf16 v[14:17], v[184:187], v[224:227], v[14:17]
	v_mfma_f32_16x16x32_bf16 v[6:9], v[172:175], v[228:231], v[6:9]
	v_mfma_f32_16x16x32_bf16 v[6:9], v[176:179], v[232:235], v[6:9]
	v_mfma_f32_16x16x32_bf16 v[2:5], v[180:183], v[228:231], v[2:5]
	v_mfma_f32_16x16x32_bf16 v[2:5], v[184:187], v[232:235], v[2:5]
	s_barrier
	s_add_i32 s10, 0, 0x18000
	s_add_i32 s11, 0, 0x1c000
	v_add_u32_e32 v168, s10, v157
	v_add_u32_e32 v184, s11, v157
	ds_read_b128 v[152:155], v168
	ds_read_b128 v[160:163], v168 offset:1024
	ds_read_b128 v[164:167], v168 offset:2048
	ds_read_b128 v[168:171], v168 offset:3072
	ds_read_b128 v[172:175], v184
	ds_read_b128 v[176:179], v184 offset:1024
	ds_read_b128 v[180:183], v184 offset:2048
	ds_read_b128 v[184:187], v184 offset:3072
	s_add_u32 s38, s50, 0x80000
	s_addc_u32 s39, s51, 0
	s_mov_b32 m0, s59
	v_lshl_add_u64 v[242:243], s[38:39], 0, v[146:147]
	ds_read_b128 v[188:191], v159 offset:32768
	ds_read_b128 v[192:195], v159 offset:33792
	ds_read_b128 v[196:199], v159 offset:34816
	ds_read_b128 v[216:219], v159 offset:35840
	ds_read_b128 v[220:223], v159 offset:36864
	ds_read_b128 v[224:227], v159 offset:37888
	ds_read_b128 v[228:231], v159 offset:38912
	ds_read_b128 v[232:235], v159 offset:39936
	global_load_lds_dwordx4 v[242:243], off
	v_lshl_add_u64 v[242:243], s[38:39], 0, v[144:145]
	s_mov_b32 m0, s60
	s_nop 0
	global_load_lds_dwordx4 v[242:243], off
	s_waitcnt vmcnt(8) lgkmcnt(0)
	s_barrier
	v_mfma_f32_16x16x32_bf16 v[126:129], v[152:155], v[188:191], v[126:129]
	v_mfma_f32_16x16x32_bf16 v[126:129], v[160:163], v[192:195], v[126:129]
	v_mfma_f32_16x16x32_bf16 v[122:125], v[164:167], v[188:191], v[122:125]
	v_mfma_f32_16x16x32_bf16 v[122:125], v[168:171], v[192:195], v[122:125]
	v_mfma_f32_16x16x32_bf16 v[110:113], v[152:155], v[196:199], v[110:113]
	v_mfma_f32_16x16x32_bf16 v[110:113], v[160:163], v[216:219], v[110:113]
	v_mfma_f32_16x16x32_bf16 v[106:109], v[164:167], v[196:199], v[106:109]
	v_mfma_f32_16x16x32_bf16 v[106:109], v[168:171], v[216:219], v[106:109]
	v_mfma_f32_16x16x32_bf16 v[94:97], v[152:155], v[220:223], v[94:97]
	v_mfma_f32_16x16x32_bf16 v[94:97], v[160:163], v[224:227], v[94:97]
	v_mfma_f32_16x16x32_bf16 v[90:93], v[164:167], v[220:223], v[90:93]
	v_mfma_f32_16x16x32_bf16 v[90:93], v[168:171], v[224:227], v[90:93]
	v_mfma_f32_16x16x32_bf16 v[78:81], v[152:155], v[228:231], v[78:81]
	v_mfma_f32_16x16x32_bf16 v[78:81], v[160:163], v[232:235], v[78:81]
	v_mfma_f32_16x16x32_bf16 v[74:77], v[164:167], v[228:231], v[74:77]
	v_mfma_f32_16x16x32_bf16 v[74:77], v[168:171], v[232:235], v[74:77]
	v_mfma_f32_16x16x32_bf16 v[118:121], v[172:175], v[188:191], v[118:121]
	v_mfma_f32_16x16x32_bf16 v[118:121], v[176:179], v[192:195], v[118:121]
	v_mfma_f32_16x16x32_bf16 v[114:117], v[180:183], v[188:191], v[114:117]
	v_mfma_f32_16x16x32_bf16 v[114:117], v[184:187], v[192:195], v[114:117]
	v_mfma_f32_16x16x32_bf16 v[102:105], v[172:175], v[196:199], v[102:105]
	v_mfma_f32_16x16x32_bf16 v[102:105], v[176:179], v[216:219], v[102:105]
	v_mfma_f32_16x16x32_bf16 v[98:101], v[180:183], v[196:199], v[98:101]
	v_mfma_f32_16x16x32_bf16 v[98:101], v[184:187], v[216:219], v[98:101]
	v_mfma_f32_16x16x32_bf16 v[86:89], v[172:175], v[220:223], v[86:89]
	v_mfma_f32_16x16x32_bf16 v[86:89], v[176:179], v[224:227], v[86:89]
	v_mfma_f32_16x16x32_bf16 v[82:85], v[180:183], v[220:223], v[82:85]
	v_mfma_f32_16x16x32_bf16 v[82:85], v[184:187], v[224:227], v[82:85]
	v_mfma_f32_16x16x32_bf16 v[70:73], v[172:175], v[228:231], v[70:73]
	v_mfma_f32_16x16x32_bf16 v[70:73], v[176:179], v[232:235], v[70:73]
	v_mfma_f32_16x16x32_bf16 v[66:69], v[180:183], v[228:231], v[66:69]
	v_mfma_f32_16x16x32_bf16 v[66:69], v[184:187], v[232:235], v[66:69]
	s_barrier
; #define PG8_STAGE(bufoff, gbase, voff) do { _Pragma("unroll") for (int _i = 0; _i < 2; ++_i) \
;         __builtin_amdgcn_global_load_lds((const unsigned*)((const char*)(gbase) + (voff)[_i]), (PG8_LAS unsigned*)(lds + (bufoff) + ldsw + _i * 8192), 16, 0, 0); } while (0)
; #define PG8_LDA(dst, b, h) do { _Pragma("unroll") for (int m = 0; m < 4; ++m) _Pragma("unroll") for (int k = 0; k < 2; ++k) dst[m][k] = *(const PG8_LAS bf16x8*)(lds + PG8_SA(b, h) + aoff + m * 2048 + k * 1024); } while (0)
; #define PG8_WAIT_V(n) asm volatile("s_waitcnt vmcnt(" #n ")" ::: "memory")
; template <class Epi, class Sched, bool ALIGN_EPI = false, bool SP2 = false>
; __device__ __forceinline__ void gemm_phase(PG8_LAS unsigned char* lds, const Gemm g, const Sched& S, const Epi& E) {
;     ...
;             PG8_LDA(At, 1, 1); PG8_STAGE(PG8_SB(1, 0), b3, voffB); PG8_STAGE(PG8_SB(1, 1), b3 + hstep, voffB); PG8_STAGE(PG8_SA(1, 0), a3, voffA);
;             PG8_WAIT_V(8); PG8_WAIT_L(0); PG8_BAR; PG8_MMA(1, 0, At, B0); PG8_MMA(1, 1, At, B1); PG8_BAR; PG8_SCHED;
;             } else {
;             PG8_LDB(B0, 0, 0); PG8_SCHED; PG8_LDA(At, 0, 0); PG8_STAGE(PG8_SA(1, 1), a1 + hstep, voffA);
;             PG8_WAIT_L(8); PG8_BAR; PG8_WAIT_L(0); PG8_MMA(0, 0, At, B0); PG8_BAR; PG8_SCHED;
;             PG8_LDB(B1, 0, 1); PG8_STAGE(PG8_SB(0, 0), b2, voffB);
;             PG8_BAR; PG8_WAIT_L(0); PG8_MMA(0, 1, At, B1); PG8_BAR;
;             PG8_LDA(At, 0, 1); PG8_STAGE(PG8_SA(0, 0), a2, voffA);
;             PG8_BAR; PG8_WAIT_L(0); PG8_MMA(1, 0, At, B0); PG8_BAR; PG8_SCHED;
;             PG8_STAGE(PG8_SB(0, 1), b2 + hstep, voffB);
;             PG8_WAIT_V(6); PG8_BAR; PG8_MMA(1, 1, At, B1); PG8_BAR;
;             PG8_LDB(B0, 1, 0); PG8_SCHED; PG8_LDA(At, 1, 0); PG8_STAGE(PG8_SA(0, 1), a2 + hstep, voffA);
;             PG8_WAIT_L(8); PG8_BAR; PG8_WAIT_L(0); PG8_MMA(0, 0, At, B0); PG8_BAR; PG8_SCHED;
;             PG8_LDB(B1, 1, 1); PG8_STAGE(PG8_SB(1, 0), b3, voffB);
;             PG8_BAR; PG8_WAIT_L(0); PG8_MMA(0, 1, At, B1); PG8_BAR;
;             PG8_LDA(At, 1, 1); PG8_STAGE(PG8_SA(1, 0), a3, voffA);
;             PG8_BAR; PG8_WAIT_L(0); PG8_MMA(1, 0, At, B0); PG8_BAR; PG8_SCHED;
;             PG8_STAGE(PG8_SB(1, 1), b3 + hstep, voffB);
;             PG8_WAIT_V(6); PG8_BAR; PG8_MMA(1, 1, At, B1); PG8_BAR;
;             }
;         }
;         if constexpr (ALIGN_EPI) { if (wr == 0) PG8_BAR; }
	s_add_i32 s10, s10, s56
	v_lshl_add_u64 v[200:201], v[200:201], 0, s[30:31]
	s_mov_b32 m0, s10
	ds_read_b128 v[188:191], v159 offset:49152
	ds_read_b128 v[192:195], v159 offset:50176
	ds_read_b128 v[196:199], v159 offset:51200
	ds_read_b128 v[216:219], v159 offset:52224
	ds_read_b128 v[220:223], v159 offset:53248
	ds_read_b128 v[224:227], v159 offset:54272
	ds_read_b128 v[228:231], v159 offset:55296
	ds_read_b128 v[232:235], v159 offset:56320
	global_load_lds_dwordx4 v[200:201], off
	s_add_i32 m0, s10, 0x2000
	s_add_u32 s18, s18, 0x80080
	v_lshl_add_u64 v[200:201], v[236:237], 0, s[30:31]
	s_addc_u32 s19, s19, 0
	s_add_i32 s10, s11, s56
	global_load_lds_dwordx4 v[200:201], off
	v_lshl_add_u64 v[200:201], s[18:19], 0, v[0:1]
	s_mov_b32 m0, s10
	s_nop 0
	global_load_lds_dwordx4 v[200:201], off
	v_lshl_add_u64 v[200:201], s[18:19], 0, v[142:143]
	s_add_i32 m0, s10, 0x2000
	s_nop 0
	global_load_lds_dwordx4 v[200:201], off
	v_lshl_add_u64 v[200:201], v[238:239], 0, s[30:31]
	s_mov_b32 m0, s61
	s_nop 0
	global_load_lds_dwordx4 v[200:201], off
	v_lshl_add_u64 v[200:201], v[240:241], 0, s[30:31]
	s_mov_b32 m0, s62
	s_nop 0
	global_load_lds_dwordx4 v[200:201], off
	s_waitcnt vmcnt(8) lgkmcnt(0)
	s_barrier
	v_mfma_f32_16x16x32_bf16 v[62:65], v[152:155], v[188:191], v[62:65]
	v_mfma_f32_16x16x32_bf16 v[62:65], v[160:163], v[192:195], v[62:65]
	v_mfma_f32_16x16x32_bf16 v[58:61], v[164:167], v[188:191], v[58:61]
	v_mfma_f32_16x16x32_bf16 v[58:61], v[168:171], v[192:195], v[58:61]
	v_mfma_f32_16x16x32_bf16 v[50:53], v[152:155], v[196:199], v[50:53]
	v_mfma_f32_16x16x32_bf16 v[50:53], v[160:163], v[216:219], v[50:53]
	v_mfma_f32_16x16x32_bf16 v[42:45], v[164:167], v[196:199], v[42:45]
	v_mfma_f32_16x16x32_bf16 v[42:45], v[168:171], v[216:219], v[42:45]
	v_mfma_f32_16x16x32_bf16 v[34:37], v[152:155], v[220:223], v[34:37]
	v_mfma_f32_16x16x32_bf16 v[34:37], v[160:163], v[224:227], v[34:37]
	v_mfma_f32_16x16x32_bf16 v[26:29], v[164:167], v[220:223], v[26:29]
	v_mfma_f32_16x16x32_bf16 v[26:29], v[168:171], v[224:227], v[26:29]
	v_mfma_f32_16x16x32_bf16 v[18:21], v[152:155], v[228:231], v[18:21]
	v_mfma_f32_16x16x32_bf16 v[18:21], v[160:163], v[232:235], v[18:21]
	v_mfma_f32_16x16x32_bf16 v[10:13], v[164:167], v[228:231], v[10:13]
	v_mfma_f32_16x16x32_bf16 v[10:13], v[168:171], v[232:235], v[10:13]
	v_mfma_f32_16x16x32_bf16 v[54:57], v[172:175], v[188:191], v[54:57]
	v_mfma_f32_16x16x32_bf16 v[54:57], v[176:179], v[192:195], v[54:57]
	v_mfma_f32_16x16x32_bf16 v[46:49], v[180:183], v[188:191], v[46:49]
	v_mfma_f32_16x16x32_bf16 v[46:49], v[184:187], v[192:195], v[46:49]
	v_mfma_f32_16x16x32_bf16 v[38:41], v[172:175], v[196:199], v[38:41]
	v_mfma_f32_16x16x32_bf16 v[38:41], v[176:179], v[216:219], v[38:41]
	v_mfma_f32_16x16x32_bf16 v[30:33], v[180:183], v[196:199], v[30:33]
	v_mfma_f32_16x16x32_bf16 v[30:33], v[184:187], v[216:219], v[30:33]
	v_mfma_f32_16x16x32_bf16 v[22:25], v[172:175], v[220:223], v[22:25]
	v_mfma_f32_16x16x32_bf16 v[22:25], v[176:179], v[224:227], v[22:25]
	v_mfma_f32_16x16x32_bf16 v[14:17], v[180:183], v[220:223], v[14:17]
	v_mfma_f32_16x16x32_bf16 v[14:17], v[184:187], v[224:227], v[14:17]
	v_mfma_f32_16x16x32_bf16 v[6:9], v[172:175], v[228:231], v[6:9]
	v_mfma_f32_16x16x32_bf16 v[6:9], v[176:179], v[232:235], v[6:9]
	v_mfma_f32_16x16x32_bf16 v[2:5], v[180:183], v[228:231], v[2:5]
	v_mfma_f32_16x16x32_bf16 v[2:5], v[184:187], v[232:235], v[2:5]
	s_barrier
	s_add_i32 s23, s23, 2
	s_add_u32 s16, s16, 0x100
	s_addc_u32 s17, s17, 0
	s_add_u32 s15, s15, 0x100
	s_addc_u32 s22, s22, 0
	s_cmp_gt_u32 s23, 29
	s_cbranch_scc0 .LBB0_265
	s_and_b64 vcc, exec, s[24:25]
	s_cbranch_vccz .LBB0_268
	s_barrier

; #define PG8_STAGE(bufoff, gbase, voff) do { _Pragma("unroll") for (int _i = 0; _i < 2; ++_i) \
;         __builtin_amdgcn_global_load_lds((const unsigned*)((const char*)(gbase) + (voff)[_i]), (PG8_LAS unsigned*)(lds + (bufoff) + ldsw + _i * 8192), 16, 0, 0); } while (0)
; #define PG8_LDA(dst, b, h) do { _Pragma("unroll") for (int m = 0; m < 4; ++m) _Pragma("unroll") for (int k = 0; k < 2; ++k) dst[m][k] = *(const PG8_LAS bf16x8*)(lds + PG8_SA(b, h) + aoff + m * 2048 + k * 1024); } while (0)
; #define PG8_LDB(dst, b, h) do { _Pragma("unroll") for (int n = 0; n < 2; ++n) _Pragma("unroll") for (int k = 0; k < 2; ++k) dst[n][k] = *(const PG8_LAS bf16x8*)(lds + PG8_SB(b, h) + boff + n * 2048 + k * 1024); } while (0)
; #define PG8_MMA(ai, bj, At, Bt) do { __builtin_amdgcn_s_setprio(1); _Pragma("unroll") for (int m = 0; m < 4; ++m) _Pragma("unroll") for (int n = 0; n < 2; ++n) _Pragma("unroll") for (int k = 0; k < 2; ++k) \
;         acc[ai][bj][m][n] = __builtin_amdgcn_mfma_f32_16x16x32_bf16(Bt[n][k], At[m][k], acc[ai][bj][m][n], 0, 0, 0); __builtin_amdgcn_s_setprio(0); } while (0)
; #define PG8_WAIT_V(n) asm volatile("s_waitcnt vmcnt(" #n ")" ::: "memory")
; #define PG8_WAIT_L(n) asm volatile("s_waitcnt lgkmcnt(" #n ")" ::: "memory")
; #define PG8_BAR __builtin_amdgcn_s_barrier()
; #define PG8_SCHED __builtin_amdgcn_sched_barrier(0)
; template <class Epi, class Sched, bool ALIGN_EPI = false, bool SP2 = false>
; __device__ __forceinline__ void gemm_phase(PG8_LAS unsigned char* lds, const Gemm g, const Sched& S, const Epi& E) {
;     ...
;             PG8_LDB(B0, 0, 0); PG8_LDB(B1, 0, 1); PG8_SCHED; PG8_LDA(At, 0, 0); PG8_STAGE(PG8_SA(1, 1), a1 + hstep, voffA);
;             PG8_WAIT_V(8); PG8_WAIT_L(0); PG8_BAR; PG8_MMA(0, 0, At, B0); PG8_MMA(0, 1, At, B1); PG8_BAR; PG8_SCHED;
;             PG8_LDA(At, 0, 1); PG8_STAGE(PG8_SB(0, 0), b2, voffB); PG8_STAGE(PG8_SB(0, 1), b2 + hstep, voffB); PG8_STAGE(PG8_SA(0, 0), a2, voffA);
;             PG8_WAIT_V(8); PG8_WAIT_L(0); PG8_BAR; PG8_MMA(1, 0, At, B0); PG8_MMA(1, 1, At, B1); PG8_BAR; PG8_SCHED;
.LBB0_601:
	s_add_u32 s18, s16, 0x100
	s_addc_u32 s19, s17, 0
	s_add_i32 s10, 0, 0x10000
	s_cmp_eq_u32 s22, 28
	s_cselect_b32 s27, s5, s19
	s_cselect_b32 s26, s7, s18
	s_cselect_b32 s25, s8, s15
	s_cselect_b32 s24, s9, s14
	s_add_i32 s12, 0, 0x14000
	v_add_u32_e32 v160, s10, v187
	v_add_u32_e32 v176, s12, v187
	ds_read_b128 v[148:151], v160
	ds_read_b128 v[152:155], v160 offset:1024
	ds_read_b128 v[156:159], v160 offset:2048
	ds_read_b128 v[160:163], v160 offset:3072
	ds_read_b128 v[164:167], v176
	ds_read_b128 v[168:171], v176 offset:1024
	ds_read_b128 v[172:175], v176 offset:2048
	ds_read_b128 v[176:179], v176 offset:3072
	v_lshl_add_u64 v[184:185], s[16:17], 0, v[144:145]
	s_add_i32 m0, s61, 0xc000
	ds_read_b128 v[180:183], v189
	ds_read_b128 v[190:193], v189 offset:1024
	ds_read_b128 v[194:197], v189 offset:2048
	ds_read_b128 v[198:201], v189 offset:3072
	ds_read_b128 v[216:219], v189 offset:4096
	ds_read_b128 v[220:223], v189 offset:5120
	ds_read_b128 v[224:227], v189 offset:6144
	ds_read_b128 v[228:231], v189 offset:7168
	global_load_lds_dwordx4 v[184:185], off
	v_lshl_add_u64 v[184:185], s[16:17], 0, v[146:147]
	s_add_i32 m0, s61, 0xe000
	s_nop 0
	global_load_lds_dwordx4 v[184:185], off
	s_waitcnt vmcnt(8) lgkmcnt(0)
	s_barrier
	v_mfma_f32_16x16x32_bf16 v[126:129], v[148:151], v[180:183], v[126:129]
	v_mfma_f32_16x16x32_bf16 v[126:129], v[152:155], v[190:193], v[126:129]
	v_mfma_f32_16x16x32_bf16 v[122:125], v[156:159], v[180:183], v[122:125]
	v_mfma_f32_16x16x32_bf16 v[122:125], v[160:163], v[190:193], v[122:125]
	v_mfma_f32_16x16x32_bf16 v[110:113], v[148:151], v[194:197], v[110:113]
	v_mfma_f32_16x16x32_bf16 v[110:113], v[152:155], v[198:201], v[110:113]
	v_mfma_f32_16x16x32_bf16 v[106:109], v[156:159], v[194:197], v[106:109]
	v_mfma_f32_16x16x32_bf16 v[106:109], v[160:163], v[198:201], v[106:109]
	v_mfma_f32_16x16x32_bf16 v[94:97], v[148:151], v[216:219], v[94:97]
	v_mfma_f32_16x16x32_bf16 v[94:97], v[152:155], v[220:223], v[94:97]
	v_mfma_f32_16x16x32_bf16 v[90:93], v[156:159], v[216:219], v[90:93]
	v_mfma_f32_16x16x32_bf16 v[90:93], v[160:163], v[220:223], v[90:93]
	v_mfma_f32_16x16x32_bf16 v[78:81], v[148:151], v[224:227], v[78:81]
	v_mfma_f32_16x16x32_bf16 v[78:81], v[152:155], v[228:231], v[78:81]
	v_mfma_f32_16x16x32_bf16 v[74:77], v[156:159], v[224:227], v[74:77]
	v_mfma_f32_16x16x32_bf16 v[74:77], v[160:163], v[228:231], v[74:77]
	v_mfma_f32_16x16x32_bf16 v[118:121], v[164:167], v[180:183], v[118:121]
	v_mfma_f32_16x16x32_bf16 v[118:121], v[168:171], v[190:193], v[118:121]
	v_mfma_f32_16x16x32_bf16 v[114:117], v[172:175], v[180:183], v[114:117]
	v_mfma_f32_16x16x32_bf16 v[114:117], v[176:179], v[190:193], v[114:117]
	v_mfma_f32_16x16x32_bf16 v[102:105], v[164:167], v[194:197], v[102:105]
	v_mfma_f32_16x16x32_bf16 v[102:105], v[168:171], v[198:201], v[102:105]
	v_mfma_f32_16x16x32_bf16 v[98:101], v[172:175], v[194:197], v[98:101]
	v_mfma_f32_16x16x32_bf16 v[98:101], v[176:179], v[198:201], v[98:101]
	v_mfma_f32_16x16x32_bf16 v[86:89], v[164:167], v[216:219], v[86:89]
	v_mfma_f32_16x16x32_bf16 v[86:89], v[168:171], v[220:223], v[86:89]
	v_mfma_f32_16x16x32_bf16 v[82:85], v[172:175], v[216:219], v[82:85]
	v_mfma_f32_16x16x32_bf16 v[82:85], v[176:179], v[220:223], v[82:85]
	v_mfma_f32_16x16x32_bf16 v[70:73], v[164:167], v[224:227], v[70:73]
	v_mfma_f32_16x16x32_bf16 v[70:73], v[168:171], v[228:231], v[70:73]
	v_mfma_f32_16x16x32_bf16 v[66:69], v[172:175], v[224:227], v[66:69]
	v_mfma_f32_16x16x32_bf16 v[66:69], v[176:179], v[228:231], v[66:69]
	s_barrier
	s_add_i32 s10, s10, s60
	v_lshl_add_u64 v[184:185], s[24:25], 0, v[0:1]
	s_mov_b32 m0, s10
	ds_read_b128 v[180:183], v189 offset:16384
	ds_read_b128 v[190:193], v189 offset:17408
	ds_read_b128 v[194:197], v189 offset:18432
	ds_read_b128 v[198:201], v189 offset:19456
	ds_read_b128 v[216:219], v189 offset:20480
	ds_read_b128 v[220:223], v189 offset:21504
	ds_read_b128 v[224:227], v189 offset:22528
	ds_read_b128 v[228:231], v189 offset:23552
	global_load_lds_dwordx4 v[184:185], off
	s_add_i32 m0, s10, 0x2000
	s_add_u32 s10, s24, 0x80000
	v_lshl_add_u64 v[232:233], s[24:25], 0, v[142:143]
	s_addc_u32 s11, s25, 0
	s_add_i32 s12, s12, s60
	global_load_lds_dwordx4 v[232:233], off
	v_lshl_add_u64 v[234:235], s[10:11], 0, v[0:1]
	s_mov_b32 m0, s12
	v_lshl_add_u64 v[236:237], s[26:27], 0, v[142:143]
	global_load_lds_dwordx4 v[234:235], off
	v_lshl_add_u64 v[234:235], s[10:11], 0, v[142:143]
	s_add_i32 m0, s12, 0x2000
	s_nop 0
	global_load_lds_dwordx4 v[234:235], off
	v_lshl_add_u64 v[234:235], s[26:27], 0, v[0:1]
	s_mov_b32 m0, s61
	s_nop 0
	global_load_lds_dwordx4 v[234:235], off
	s_mov_b32 m0, s62
	s_nop 0
	global_load_lds_dwordx4 v[236:237], off
	s_waitcnt vmcnt(8) lgkmcnt(0)
	s_barrier
; #define PG8_STAGE(bufoff, gbase, voff) do { _Pragma("unroll") for (int _i = 0; _i < 2; ++_i) \
;         __builtin_amdgcn_global_load_lds((const unsigned*)((const char*)(gbase) + (voff)[_i]), (PG8_LAS unsigned*)(lds + (bufoff) + ldsw + _i * 8192), 16, 0, 0); } while (0)
; #define PG8_LDA(dst, b, h) do { _Pragma("unroll") for (int m = 0; m < 4; ++m) _Pragma("unroll") for (int k = 0; k < 2; ++k) dst[m][k] = *(const PG8_LAS bf16x8*)(lds + PG8_SA(b, h) + aoff + m * 2048 + k * 1024); } while (0)
; #define PG8_LDB(dst, b, h) do { _Pragma("unroll") for (int n = 0; n < 2; ++n) _Pragma("unroll") for (int k = 0; k < 2; ++k) dst[n][k] = *(const PG8_LAS bf16x8*)(lds + PG8_SB(b, h) + boff + n * 2048 + k * 1024); } while (0)
; #define PG8_MMA(ai, bj, At, Bt) do { __builtin_amdgcn_s_setprio(1); _Pragma("unroll") for (int m = 0; m < 4; ++m) _Pragma("unroll") for (int n = 0; n < 2; ++n) _Pragma("unroll") for (int k = 0; k < 2; ++k) \
;         acc[ai][bj][m][n] = __builtin_amdgcn_mfma_f32_16x16x32_bf16(Bt[n][k], At[m][k], acc[ai][bj][m][n], 0, 0, 0); __builtin_amdgcn_s_setprio(0); } while (0)
; #define PG8_WAIT_V(n) asm volatile("s_waitcnt vmcnt(" #n ")" ::: "memory")
; #define PG8_WAIT_L(n) asm volatile("s_waitcnt lgkmcnt(" #n ")" ::: "memory")
; #define PG8_BAR __builtin_amdgcn_s_barrier()
; #define PG8_SCHED __builtin_amdgcn_sched_barrier(0)
; template <class Epi, class Sched, bool ALIGN_EPI = false, bool SP2 = false>
; __device__ __forceinline__ void gemm_phase(PG8_LAS unsigned char* lds, const Gemm g, const Sched& S, const Epi& E) {
;     ...
;             PG8_WAIT_V(8); PG8_WAIT_L(0); PG8_BAR; PG8_MMA(1, 0, At, B0); PG8_MMA(1, 1, At, B1); PG8_BAR; PG8_SCHED;
;             PG8_LDB(B0, 1, 0); PG8_LDB(B1, 1, 1); PG8_SCHED; PG8_LDA(At, 1, 0); PG8_STAGE(PG8_SA(0, 1), a2 + hstep, voffA);
;             PG8_WAIT_V(8); PG8_WAIT_L(0); PG8_BAR; PG8_MMA(0, 0, At, B0); PG8_MMA(0, 1, At, B1); PG8_BAR; PG8_SCHED;
;             PG8_LDA(At, 1, 1); PG8_STAGE(PG8_SB(1, 0), b3, voffB); PG8_STAGE(PG8_SB(1, 1), b3 + hstep, voffB); PG8_STAGE(PG8_SA(1, 0), a3, voffA);
;             PG8_WAIT_V(8); PG8_WAIT_L(0); PG8_BAR; PG8_MMA(1, 0, At, B0); PG8_MMA(1, 1, At, B1); PG8_BAR; PG8_SCHED;
	v_mfma_f32_16x16x32_bf16 v[62:65], v[148:151], v[180:183], v[62:65]
	v_mfma_f32_16x16x32_bf16 v[62:65], v[152:155], v[190:193], v[62:65]
	v_mfma_f32_16x16x32_bf16 v[58:61], v[156:159], v[180:183], v[58:61]
	v_mfma_f32_16x16x32_bf16 v[58:61], v[160:163], v[190:193], v[58:61]
	v_mfma_f32_16x16x32_bf16 v[46:49], v[148:151], v[194:197], v[46:49]
	v_mfma_f32_16x16x32_bf16 v[46:49], v[152:155], v[198:201], v[46:49]
	v_mfma_f32_16x16x32_bf16 v[42:45], v[156:159], v[194:197], v[42:45]
	v_mfma_f32_16x16x32_bf16 v[42:45], v[160:163], v[198:201], v[42:45]
	v_mfma_f32_16x16x32_bf16 v[30:33], v[148:151], v[216:219], v[30:33]
	v_mfma_f32_16x16x32_bf16 v[30:33], v[152:155], v[220:223], v[30:33]
	v_mfma_f32_16x16x32_bf16 v[26:29], v[156:159], v[216:219], v[26:29]
	v_mfma_f32_16x16x32_bf16 v[26:29], v[160:163], v[220:223], v[26:29]
	v_mfma_f32_16x16x32_bf16 v[14:17], v[148:151], v[224:227], v[14:17]
	v_mfma_f32_16x16x32_bf16 v[14:17], v[152:155], v[228:231], v[14:17]
	v_mfma_f32_16x16x32_bf16 v[10:13], v[156:159], v[224:227], v[10:13]
	v_mfma_f32_16x16x32_bf16 v[10:13], v[160:163], v[228:231], v[10:13]
	v_mfma_f32_16x16x32_bf16 v[54:57], v[164:167], v[180:183], v[54:57]
	v_mfma_f32_16x16x32_bf16 v[54:57], v[168:171], v[190:193], v[54:57]
	v_mfma_f32_16x16x32_bf16 v[50:53], v[172:175], v[180:183], v[50:53]
	v_mfma_f32_16x16x32_bf16 v[50:53], v[176:179], v[190:193], v[50:53]
	v_mfma_f32_16x16x32_bf16 v[38:41], v[164:167], v[194:197], v[38:41]
	v_mfma_f32_16x16x32_bf16 v[38:41], v[168:171], v[198:201], v[38:41]
	v_mfma_f32_16x16x32_bf16 v[34:37], v[172:175], v[194:197], v[34:37]
	v_mfma_f32_16x16x32_bf16 v[34:37], v[176:179], v[198:201], v[34:37]
	v_mfma_f32_16x16x32_bf16 v[22:25], v[164:167], v[216:219], v[22:25]
	v_mfma_f32_16x16x32_bf16 v[22:25], v[168:171], v[220:223], v[22:25]
	v_mfma_f32_16x16x32_bf16 v[18:21], v[172:175], v[216:219], v[18:21]
	v_mfma_f32_16x16x32_bf16 v[18:21], v[176:179], v[220:223], v[18:21]
	v_mfma_f32_16x16x32_bf16 v[6:9], v[164:167], v[224:227], v[6:9]
	v_mfma_f32_16x16x32_bf16 v[6:9], v[168:171], v[228:231], v[6:9]
	v_mfma_f32_16x16x32_bf16 v[2:5], v[172:175], v[224:227], v[2:5]
	v_mfma_f32_16x16x32_bf16 v[2:5], v[176:179], v[228:231], v[2:5]
	s_barrier
	s_add_i32 s12, 0, 0x18000
	s_add_i32 s13, 0, 0x1c000
	v_add_u32_e32 v160, s12, v187
	v_add_u32_e32 v176, s13, v187
	ds_read_b128 v[148:151], v160
	ds_read_b128 v[152:155], v160 offset:1024
	ds_read_b128 v[156:159], v160 offset:2048
	ds_read_b128 v[160:163], v160 offset:3072
	ds_read_b128 v[164:167], v176
	ds_read_b128 v[168:171], v176 offset:1024
	ds_read_b128 v[172:175], v176 offset:2048
	ds_read_b128 v[176:179], v176 offset:3072
	s_add_u32 s10, s26, 0x80000
	s_addc_u32 s11, s27, 0
	s_mov_b32 m0, s63
	v_lshl_add_u64 v[238:239], s[10:11], 0, v[0:1]
	ds_read_b128 v[180:183], v189 offset:32768
	ds_read_b128 v[190:193], v189 offset:33792
	ds_read_b128 v[194:197], v189 offset:34816
	ds_read_b128 v[198:201], v189 offset:35840
	ds_read_b128 v[216:219], v189 offset:36864
	ds_read_b128 v[220:223], v189 offset:37888
	ds_read_b128 v[224:227], v189 offset:38912
	ds_read_b128 v[228:231], v189 offset:39936
	global_load_lds_dwordx4 v[238:239], off
	v_lshl_add_u64 v[238:239], s[10:11], 0, v[142:143]
	s_mov_b32 m0, s64
	s_nop 0
	global_load_lds_dwordx4 v[238:239], off
	s_waitcnt vmcnt(8) lgkmcnt(0)
	s_barrier
	v_mfma_f32_16x16x32_bf16 v[126:129], v[148:151], v[180:183], v[126:129]
	v_mfma_f32_16x16x32_bf16 v[126:129], v[152:155], v[190:193], v[126:129]
	v_mfma_f32_16x16x32_bf16 v[122:125], v[156:159], v[180:183], v[122:125]
	v_mfma_f32_16x16x32_bf16 v[122:125], v[160:163], v[190:193], v[122:125]
	v_mfma_f32_16x16x32_bf16 v[110:113], v[148:151], v[194:197], v[110:113]
	v_mfma_f32_16x16x32_bf16 v[110:113], v[152:155], v[198:201], v[110:113]
	v_mfma_f32_16x16x32_bf16 v[106:109], v[156:159], v[194:197], v[106:109]
	v_mfma_f32_16x16x32_bf16 v[106:109], v[160:163], v[198:201], v[106:109]
	v_mfma_f32_16x16x32_bf16 v[94:97], v[148:151], v[216:219], v[94:97]
	v_mfma_f32_16x16x32_bf16 v[94:97], v[152:155], v[220:223], v[94:97]
	v_mfma_f32_16x16x32_bf16 v[90:93], v[156:159], v[216:219], v[90:93]
	v_mfma_f32_16x16x32_bf16 v[90:93], v[160:163], v[220:223], v[90:93]
	v_mfma_f32_16x16x32_bf16 v[78:81], v[148:151], v[224:227], v[78:81]
	v_mfma_f32_16x16x32_bf16 v[78:81], v[152:155], v[228:231], v[78:81]
	v_mfma_f32_16x16x32_bf16 v[74:77], v[156:159], v[224:227], v[74:77]
	v_mfma_f32_16x16x32_bf16 v[74:77], v[160:163], v[228:231], v[74:77]
	v_mfma_f32_16x16x32_bf16 v[118:121], v[164:167], v[180:183], v[118:121]
	v_mfma_f32_16x16x32_bf16 v[118:121], v[168:171], v[190:193], v[118:121]
	v_mfma_f32_16x16x32_bf16 v[114:117], v[172:175], v[180:183], v[114:117]
	v_mfma_f32_16x16x32_bf16 v[114:117], v[176:179], v[190:193], v[114:117]
	v_mfma_f32_16x16x32_bf16 v[102:105], v[164:167], v[194:197], v[102:105]
	v_mfma_f32_16x16x32_bf16 v[102:105], v[168:171], v[198:201], v[102:105]
	v_mfma_f32_16x16x32_bf16 v[98:101], v[172:175], v[194:197], v[98:101]
	v_mfma_f32_16x16x32_bf16 v[98:101], v[176:179], v[198:201], v[98:101]
	v_mfma_f32_16x16x32_bf16 v[86:89], v[164:167], v[216:219], v[86:89]
	v_mfma_f32_16x16x32_bf16 v[86:89], v[168:171], v[220:223], v[86:89]
	v_mfma_f32_16x16x32_bf16 v[82:85], v[172:175], v[216:219], v[82:85]
	v_mfma_f32_16x16x32_bf16 v[82:85], v[176:179], v[220:223], v[82:85]
	v_mfma_f32_16x16x32_bf16 v[70:73], v[164:167], v[224:227], v[70:73]
	v_mfma_f32_16x16x32_bf16 v[70:73], v[168:171], v[228:231], v[70:73]
	v_mfma_f32_16x16x32_bf16 v[66:69], v[172:175], v[224:227], v[66:69]
	v_mfma_f32_16x16x32_bf16 v[66:69], v[176:179], v[228:231], v[66:69]
	s_barrier
; #define PG8_STAGE(bufoff, gbase, voff) do { _Pragma("unroll") for (int _i = 0; _i < 2; ++_i) \
;         __builtin_amdgcn_global_load_lds((const unsigned*)((const char*)(gbase) + (voff)[_i]), (PG8_LAS unsigned*)(lds + (bufoff) + ldsw + _i * 8192), 16, 0, 0); } while (0)
; #define PG8_LDA(dst, b, h) do { _Pragma("unroll") for (int m = 0; m < 4; ++m) _Pragma("unroll") for (int k = 0; k < 2; ++k) dst[m][k] = *(const PG8_LAS bf16x8*)(lds + PG8_SA(b, h) + aoff + m * 2048 + k * 1024); } while (0)
; #define PG8_LDB(dst, b, h) do { _Pragma("unroll") for (int n = 0; n < 2; ++n) _Pragma("unroll") for (int k = 0; k < 2; ++k) dst[n][k] = *(const PG8_LAS bf16x8*)(lds + PG8_SB(b, h) + boff + n * 2048 + k * 1024); } while (0)
; template <class Epi, class Sched, bool ALIGN_EPI = false, bool SP2 = false>
; __device__ __forceinline__ void gemm_phase(PG8_LAS unsigned char* lds, const Gemm g, const Sched& S, const Epi& E) {
;     ...
;         for (int t = 0; t < nt; t += 2) {
;             const bool last = (t == nt - 2);
;             const char* a1 = cA + (size_t)(t + 1) * kstep;
;             const char* a2 = last ? nA : cA + (size_t)(t + 2) * kstep; const char* b2 = last ? nB : cB + (size_t)(t + 2) * kstep;
;             const char* a3 = a2 + kstep; const char* b3 = b2 + kstep;
;             if (last && has_next) S.a_ready(nxt);
;             if constexpr (SP2) {
;             PG8_LDB(B0, 0, 0); PG8_LDB(B1, 0, 1); PG8_SCHED; PG8_LDA(At, 0, 0); PG8_STAGE(PG8_SA(1, 1), a1 + hstep, voffA);
;             PG8_WAIT_V(8); PG8_WAIT_L(0); PG8_BAR; PG8_MMA(0, 0, At, B0); PG8_MMA(0, 1, At, B1); PG8_BAR; PG8_SCHED;
;             PG8_LDA(At, 0, 1); PG8_STAGE(PG8_SB(0, 0), b2, voffB); PG8_STAGE(PG8_SB(0, 1), b2 + hstep, voffB); PG8_STAGE(PG8_SA(0, 0), a2, voffA);
;             PG8_WAIT_V(8); PG8_WAIT_L(0); PG8_BAR; PG8_MMA(1, 0, At, B0); PG8_MMA(1, 1, At, B1); PG8_BAR; PG8_SCHED;
;             PG8_LDB(B0, 1, 0); PG8_LDB(B1, 1, 1); PG8_SCHED; PG8_LDA(At, 1, 0); PG8_STAGE(PG8_SA(0, 1), a2 + hstep, voffA);
;             PG8_WAIT_V(8); PG8_WAIT_L(0); PG8_BAR; PG8_MMA(0, 0, At, B0); PG8_MMA(0, 1, At, B1); PG8_BAR; PG8_SCHED;
;             PG8_LDA(At, 1, 1); PG8_STAGE(PG8_SB(1, 0), b3, voffB); PG8_STAGE(PG8_SB(1, 1), b3 + hstep, voffB); PG8_STAGE(PG8_SA(1, 0), a3, voffA);
;             PG8_WAIT_V(8); PG8_WAIT_L(0); PG8_BAR; PG8_MMA(1, 0, At, B0); PG8_MMA(1, 1, At, B1); PG8_BAR; PG8_SCHED;
	s_add_i32 s10, s12, s60
	v_lshl_add_u64 v[184:185], v[184:185], 0, s[30:31]
	s_mov_b32 m0, s10
	ds_read_b128 v[180:183], v189 offset:49152
	ds_read_b128 v[190:193], v189 offset:50176
	ds_read_b128 v[194:197], v189 offset:51200
	ds_read_b128 v[198:201], v189 offset:52224
	ds_read_b128 v[216:219], v189 offset:53248
	ds_read_b128 v[220:223], v189 offset:54272
	ds_read_b128 v[224:227], v189 offset:55296
	ds_read_b128 v[228:231], v189 offset:56320
	global_load_lds_dwordx4 v[184:185], off
	s_add_i32 m0, s10, 0x2000
	s_add_u32 s10, s24, 0x80080
	v_lshl_add_u64 v[184:185], v[232:233], 0, s[30:31]
	s_addc_u32 s11, s25, 0
	s_add_i32 s12, s13, s60
	global_load_lds_dwordx4 v[184:185], off
	v_lshl_add_u64 v[184:185], s[10:11], 0, v[0:1]
	s_mov_b32 m0, s12
	s_nop 0
	global_load_lds_dwordx4 v[184:185], off
	v_lshl_add_u64 v[184:185], s[10:11], 0, v[142:143]
	s_add_i32 m0, s12, 0x2000
	s_nop 0
	global_load_lds_dwordx4 v[184:185], off
	v_lshl_add_u64 v[184:185], v[234:235], 0, s[30:31]
	s_mov_b32 m0, s65
	s_nop 0
	global_load_lds_dwordx4 v[184:185], off
	v_lshl_add_u64 v[184:185], v[236:237], 0, s[30:31]
	s_mov_b32 m0, s66
	s_nop 0
	global_load_lds_dwordx4 v[184:185], off
	s_waitcnt vmcnt(8) lgkmcnt(0)
	s_barrier
	v_mfma_f32_16x16x32_bf16 v[62:65], v[148:151], v[180:183], v[62:65]
	v_mfma_f32_16x16x32_bf16 v[62:65], v[152:155], v[190:193], v[62:65]
	v_mfma_f32_16x16x32_bf16 v[58:61], v[156:159], v[180:183], v[58:61]
	v_mfma_f32_16x16x32_bf16 v[58:61], v[160:163], v[190:193], v[58:61]
	v_mfma_f32_16x16x32_bf16 v[46:49], v[148:151], v[194:197], v[46:49]
	v_mfma_f32_16x16x32_bf16 v[46:49], v[152:155], v[198:201], v[46:49]
	v_mfma_f32_16x16x32_bf16 v[42:45], v[156:159], v[194:197], v[42:45]
	v_mfma_f32_16x16x32_bf16 v[42:45], v[160:163], v[198:201], v[42:45]
	v_mfma_f32_16x16x32_bf16 v[30:33], v[148:151], v[216:219], v[30:33]
	v_mfma_f32_16x16x32_bf16 v[30:33], v[152:155], v[220:223], v[30:33]
	v_mfma_f32_16x16x32_bf16 v[26:29], v[156:159], v[216:219], v[26:29]
	v_mfma_f32_16x16x32_bf16 v[26:29], v[160:163], v[220:223], v[26:29]
	v_mfma_f32_16x16x32_bf16 v[14:17], v[148:151], v[224:227], v[14:17]
	v_mfma_f32_16x16x32_bf16 v[14:17], v[152:155], v[228:231], v[14:17]
	v_mfma_f32_16x16x32_bf16 v[10:13], v[156:159], v[224:227], v[10:13]
	v_mfma_f32_16x16x32_bf16 v[10:13], v[160:163], v[228:231], v[10:13]
	v_mfma_f32_16x16x32_bf16 v[54:57], v[164:167], v[180:183], v[54:57]
	v_mfma_f32_16x16x32_bf16 v[54:57], v[168:171], v[190:193], v[54:57]
	v_mfma_f32_16x16x32_bf16 v[50:53], v[172:175], v[180:183], v[50:53]
	v_mfma_f32_16x16x32_bf16 v[50:53], v[176:179], v[190:193], v[50:53]
	v_mfma_f32_16x16x32_bf16 v[38:41], v[164:167], v[194:197], v[38:41]
	v_mfma_f32_16x16x32_bf16 v[38:41], v[168:171], v[198:201], v[38:41]
	v_mfma_f32_16x16x32_bf16 v[34:37], v[172:175], v[194:197], v[34:37]
	v_mfma_f32_16x16x32_bf16 v[34:37], v[176:179], v[198:201], v[34:37]
	v_mfma_f32_16x16x32_bf16 v[22:25], v[164:167], v[216:219], v[22:25]
	v_mfma_f32_16x16x32_bf16 v[22:25], v[168:171], v[220:223], v[22:25]
	v_mfma_f32_16x16x32_bf16 v[18:21], v[172:175], v[216:219], v[18:21]
	v_mfma_f32_16x16x32_bf16 v[18:21], v[176:179], v[220:223], v[18:21]
	v_mfma_f32_16x16x32_bf16 v[6:9], v[164:167], v[224:227], v[6:9]
	v_mfma_f32_16x16x32_bf16 v[6:9], v[168:171], v[228:231], v[6:9]
	v_mfma_f32_16x16x32_bf16 v[2:5], v[172:175], v[224:227], v[2:5]
	v_mfma_f32_16x16x32_bf16 v[2:5], v[176:179], v[228:231], v[2:5]
	s_barrier
	s_add_i32 s22, s22, 2
	s_add_u32 s14, s14, 0x100
	s_addc_u32 s15, s15, 0
	s_cmp_gt_u32 s22, 29
	s_mov_b64 s[16:17], s[18:19]
	s_cbranch_scc0 .LBB0_601
; __device__ __forceinline__ unsigned cvt_pk_bf16(float lo, float hi) { unsigned r; asm volatile("v_cvt_pk_bf16_f32 %0, %1, %2" : "=v"(r) : "v"(lo), "v"(hi)); return r; }
;     __device__ __forceinline__ void operator()(const f32x4 (&acc)[2][2][4][2], const Unit& u, int wr, int wc, int fr, int fq) const {
;     ...
;         for (int ai = 0; ai < 2; ++ai) {
;             u32x2 bv[4][2][2];
; #pragma unroll
;             for (int m = 0; m < 4; ++m) { const size_t off = (size_t)(row0 + ai * HALF + m * 16) * ldc + col0;
; #pragma unroll
;                 for (int bj = 0; bj < 2; ++bj)
; #pragma unroll
;                     for (int n = 0; n < 2; ++n) bv[m][bj][n] = *(const u32x2*)(xb + off + bj * HALF + n * 16); }
;             asm volatile("" ::: "memory");
; #pragma unroll
;             for (int m = 0; m < 4; ++m) {
;                 const int row = row0 + ai * HALF + m * 16;
;                 const size_t off = (size_t)row * ldc + col0;
;                 float s = 0.f;
; #pragma unroll
;                 for (int bj = 0; bj < 2; ++bj)
; #pragma unroll
;                     for (int n = 0; n < 2; ++n) {
;                         const size_t c = off + bj * HALF + n * 16;
;                         const u32x2 w0 = bv[m][bj][n];
;                         const f32x4 b = {__uint_as_float(w0.x << 16), __uint_as_float(w0.x & 0xffff0000u), __uint_as_float(w0.y << 16), __uint_as_float(w0.y & 0xffff0000u)};
;                         const f32x4 o = b + acc[ai][bj][m][n];
;                         if (fin) { *(f32x4*)(outf + c) = o; }
;                         else { u32x2 w; w.x = cvt_pk_bf16(o[0], o[1]); w.y = cvt_pk_bf16(o[2], o[3]); *(u32x2*)(xb + c) = w;
;                                s += (o[0] * o[0] + o[1] * o[1]) + (o[2] * o[2] + o[3] * o[3]); }
;                     }
;                 if (!fin) { s += __shfl_xor(s, 16); s += __shfl_xor(s, 32); if (fq == 0) unsafeAtomicAdd(ssq + row, s); }
	v_lshl_or_b32 v148, s2, 8, v188
	v_lshl_add_u32 v152, s4, 8, v186
	v_ashrrev_i32_e32 v149, 31, v148
	v_lshlrev_b64 v[190:191], 1, v[148:149]
	v_ashrrev_i32_e32 v153, 31, v152
	v_lshl_add_u64 v[150:151], s[48:49], 0, v[190:191]
	v_lshlrev_b64 v[154:155], 12, v[152:153]
	v_lshl_add_u64 v[156:157], v[150:151], 0, v[154:155]
	global_load_dwordx2 v[192:193], v[156:157], off
	global_load_dwordx2 v[194:195], v[156:157], off offset:32
	global_load_dwordx2 v[196:197], v[156:157], off offset:256
	global_load_dwordx2 v[198:199], v[156:157], off offset:288
	v_or_b32_e32 v184, 16, v152
	v_ashrrev_i32_e32 v185, 31, v184
	v_lshlrev_b64 v[156:157], 12, v[184:185]
	v_or_b32_e32 v174, 32, v152
	v_lshl_add_u64 v[156:157], v[150:151], 0, v[156:157]
	v_ashrrev_i32_e32 v175, 31, v174
	global_load_dwordx2 v[182:183], v[156:157], off
	global_load_dwordx2 v[180:181], v[156:157], off offset:32
	global_load_dwordx2 v[178:179], v[156:157], off offset:256
	global_load_dwordx2 v[176:177], v[156:157], off offset:288
	v_lshlrev_b64 v[156:157], 12, v[174:175]
	v_or_b32_e32 v158, 48, v152
	v_lshl_add_u64 v[156:157], v[150:151], 0, v[156:157]
	v_ashrrev_i32_e32 v159, 31, v158
	global_load_dwordx2 v[172:173], v[156:157], off
	global_load_dwordx2 v[170:171], v[156:157], off offset:32
	global_load_dwordx2 v[166:167], v[156:157], off offset:256
	global_load_dwordx2 v[162:163], v[156:157], off offset:288
	v_lshlrev_b64 v[156:157], 12, v[158:159]
	v_lshl_add_u64 v[156:157], v[150:151], 0, v[156:157]
	global_load_dwordx2 v[168:169], v[156:157], off
	global_load_dwordx2 v[164:165], v[156:157], off offset:32
	global_load_dwordx2 v[160:161], v[156:157], off offset:256
	s_nop 0
	global_load_dwordx2 v[156:157], v[156:157], off offset:288
	s_waitcnt vmcnt(0)
	v_lshlrev_b32_e32 v200, 16, v192
	v_and_b32_e32 v201, 0xffff0000, v192
	v_lshlrev_b32_e32 v192, 16, v193
	v_and_b32_e32 v193, 0xffff0000, v193
	v_pk_add_f32 v[126:127], v[126:127], v[200:201]
	v_pk_add_f32 v[128:129], v[128:129], v[192:193]
	v_cvt_pk_bf16_f32 v192, v126, v127
	v_mul_f32_e32 v127, v127, v127
	v_lshl_add_u64 v[200:201], s[48:49], 0, v[154:155]
	v_fmac_f32_e32 v127, v126, v126
	v_mul_f32_e32 v126, v129, v129
	v_lshl_add_u64 v[190:191], v[200:201], 0, v[190:191]
	v_fmac_f32_e32 v126, v128, v128
	v_cvt_pk_bf16_f32 v193, v128, v129
	global_store_dwordx2 v[190:191], v[192:193], off
	v_add_f32_e32 v192, v127, v126
	v_lshlrev_b32_e32 v126, 16, v194
	v_and_b32_e32 v127, 0xffff0000, v194
	v_lshlrev_b32_e32 v128, 16, v195
	v_and_b32_e32 v129, 0xffff0000, v195
	v_pk_add_f32 v[122:123], v[122:123], v[126:127]
	v_pk_add_f32 v[124:125], v[124:125], v[128:129]
	v_cvt_pk_bf16_f32 v126, v122, v123
	v_mul_f32_e32 v123, v123, v123
	v_fmac_f32_e32 v123, v122, v122
	v_mul_f32_e32 v122, v125, v125
	v_fmac_f32_e32 v122, v124, v124
	v_add_f32_e32 v122, v123, v122
	v_cvt_pk_bf16_f32 v127, v124, v125
	global_store_dwordx2 v[190:191], v[126:127], off offset:32
	v_add_f32_e32 v126, v192, v122
	v_lshlrev_b32_e32 v122, 16, v196
	v_and_b32_e32 v123, 0xffff0000, v196
	v_lshlrev_b32_e32 v124, 16, v197
	v_and_b32_e32 v125, 0xffff0000, v197
	v_pk_add_f32 v[118:119], v[118:119], v[122:123]
	v_pk_add_f32 v[120:121], v[120:121], v[124:125]
	v_cvt_pk_bf16_f32 v122, v118, v119
	v_mul_f32_e32 v119, v119, v119
	v_fmac_f32_e32 v119, v118, v118
	v_mul_f32_e32 v118, v121, v121
	v_fmac_f32_e32 v118, v120, v120
	v_add_f32_e32 v118, v119, v118
	v_cvt_pk_bf16_f32 v123, v120, v121
	global_store_dwordx2 v[190:191], v[122:123], off offset:256
	v_add_f32_e32 v122, v126, v118
	v_lshlrev_b32_e32 v118, 16, v198
	v_and_b32_e32 v119, 0xffff0000, v198
	v_lshlrev_b32_e32 v120, 16, v199
	v_and_b32_e32 v121, 0xffff0000, v199
	v_pk_add_f32 v[114:115], v[114:115], v[118:119]
	v_pk_add_f32 v[116:117], v[116:117], v[120:121]
	v_cvt_pk_bf16_f32 v118, v114, v115
	v_mul_f32_e32 v115, v115, v115
	v_fmac_f32_e32 v115, v114, v114
	v_mul_f32_e32 v114, v117, v117
	v_cvt_pk_bf16_f32 v119, v116, v117
	v_fmac_f32_e32 v114, v116, v116
	v_and_b32_e32 v116, 64, v208
	v_add_f32_e32 v114, v115, v114
	v_xor_b32_e32 v115, 16, v208
	v_add_u32_e32 v117, 64, v116
	v_cmp_lt_i32_e32 vcc, v115, v117
	v_add_f32_e32 v114, v122, v114
	global_store_dwordx2 v[190:191], v[118:119], off offset:288
	v_cndmask_b32_e32 v115, v208, v115, vcc
	v_lshlrev_b32_e32 v116, 2, v115
	ds_bpermute_b32 v115, v116, v114
	s_waitcnt lgkmcnt(0)
	v_add_f32_e32 v118, v114, v115
	v_xor_b32_e32 v114, 32, v208
	v_cmp_lt_i32_e32 vcc, v114, v117
	s_nop 1
	v_cndmask_b32_e32 v114, v208, v114, vcc
	v_lshlrev_b32_e32 v117, 2, v114
	ds_bpermute_b32 v119, v117, v118
	v_lshl_add_u64 v[114:115], v[152:153], 2, s[50:51]
	s_and_saveexec_b64 s[16:17], s[42:43]
	s_cbranch_execz .LBB0_604
	s_waitcnt lgkmcnt(0)
	v_add_f32_e32 v118, v118, v119
	global_atomic_add_f32 v[114:115], v118, off

; #define PG8_STAGE(bufoff, gbase, voff) do { _Pragma("unroll") for (int _i = 0; _i < 2; ++_i) \
;         __builtin_amdgcn_global_load_lds((const unsigned*)((const char*)(gbase) + (voff)[_i]), (PG8_LAS unsigned*)(lds + (bufoff) + ldsw + _i * 8192), 16, 0, 0); } while (0)
; #define PG8_LDA(dst, b, h) do { _Pragma("unroll") for (int m = 0; m < 4; ++m) _Pragma("unroll") for (int k = 0; k < 2; ++k) dst[m][k] = *(const PG8_LAS bf16x8*)(lds + PG8_SA(b, h) + aoff + m * 2048 + k * 1024); } while (0)
; #define PG8_LDB(dst, b, h) do { _Pragma("unroll") for (int n = 0; n < 2; ++n) _Pragma("unroll") for (int k = 0; k < 2; ++k) dst[n][k] = *(const PG8_LAS bf16x8*)(lds + PG8_SB(b, h) + boff + n * 2048 + k * 1024); } while (0)
; #define PG8_MMA(ai, bj, At, Bt) do { __builtin_amdgcn_s_setprio(1); _Pragma("unroll") for (int m = 0; m < 4; ++m) _Pragma("unroll") for (int n = 0; n < 2; ++n) _Pragma("unroll") for (int k = 0; k < 2; ++k) \
;         acc[ai][bj][m][n] = __builtin_amdgcn_mfma_f32_16x16x32_bf16(Bt[n][k], At[m][k], acc[ai][bj][m][n], 0, 0, 0); __builtin_amdgcn_s_setprio(0); } while (0)
; #define PG8_WAIT_V(n) asm volatile("s_waitcnt vmcnt(" #n ")" ::: "memory")
; #define PG8_WAIT_L(n) asm volatile("s_waitcnt lgkmcnt(" #n ")" ::: "memory")
; #define PG8_BAR __builtin_amdgcn_s_barrier()
; #define PG8_SCHED __builtin_amdgcn_sched_barrier(0)
; template <class Epi, class Sched, bool ALIGN_EPI = false, bool SP2 = false>
; __device__ __forceinline__ void gemm_phase(PG8_LAS unsigned char* lds, const Gemm g, const Sched& S, const Epi& E) {
;     ...
;             PG8_LDB(B0, 0, 0); PG8_LDB(B1, 0, 1); PG8_SCHED; PG8_LDA(At, 0, 0); PG8_STAGE(PG8_SA(1, 1), a1 + hstep, voffA);
;             PG8_WAIT_V(8); PG8_WAIT_L(0); PG8_BAR; PG8_MMA(0, 0, At, B0); PG8_MMA(0, 1, At, B1); PG8_BAR; PG8_SCHED;
;             PG8_LDA(At, 0, 1); PG8_STAGE(PG8_SB(0, 0), b2, voffB); PG8_STAGE(PG8_SB(0, 1), b2 + hstep, voffB); PG8_STAGE(PG8_SA(0, 0), a2, voffA);
;             PG8_WAIT_V(8); PG8_WAIT_L(0); PG8_BAR; PG8_MMA(1, 0, At, B0); PG8_MMA(1, 1, At, B1); PG8_BAR; PG8_SCHED;
.LBB0_686:
	s_add_u32 s10, s16, 0xfff80080
	s_addc_u32 s11, s17, -1
	s_add_i32 s12, 0, 0x10000
	s_cmp_eq_u32 s22, 28
	s_cselect_b32 s25, s5, s11
	s_cselect_b32 s24, s7, s10
	v_add_u32_e32 v160, s12, v163
	s_cselect_b32 s19, s8, s15
	s_cselect_b32 s18, s9, s14
	s_add_i32 s13, 0, 0x14000
	ds_read_b128 v[152:155], v160
	ds_read_b128 v[156:159], v160 offset:1024
	ds_read_b128 v[166:169], v160 offset:2048
	ds_read_b128 v[170:173], v160 offset:3072
	v_add_u32_e32 v160, s13, v163
	ds_read_b128 v[174:177], v160
	ds_read_b128 v[178:181], v160 offset:1024
	ds_read_b128 v[182:185], v160 offset:2048
	ds_read_b128 v[186:189], v160 offset:3072
	v_lshl_add_u64 v[160:161], s[16:17], 0, v[148:149]
	s_add_i32 m0, s59, 0xc000
	ds_read_b128 v[190:193], v165
	ds_read_b128 v[194:197], v165 offset:1024
	ds_read_b128 v[198:201], v165 offset:2048
	ds_read_b128 v[216:219], v165 offset:3072
	ds_read_b128 v[220:223], v165 offset:4096
	ds_read_b128 v[224:227], v165 offset:5120
	ds_read_b128 v[228:231], v165 offset:6144
	ds_read_b128 v[232:235], v165 offset:7168
	global_load_lds_dwordx4 v[160:161], off
	v_lshl_add_u64 v[160:161], s[16:17], 0, v[150:151]
	s_add_i32 m0, s59, 0xe000
	s_nop 0
	global_load_lds_dwordx4 v[160:161], off
	s_waitcnt vmcnt(8) lgkmcnt(0)
	s_barrier
	v_mfma_f32_16x16x32_bf16 v[126:129], v[152:155], v[190:193], v[126:129]
	v_mfma_f32_16x16x32_bf16 v[126:129], v[156:159], v[194:197], v[126:129]
	v_mfma_f32_16x16x32_bf16 v[122:125], v[166:169], v[190:193], v[122:125]
	v_mfma_f32_16x16x32_bf16 v[122:125], v[170:173], v[194:197], v[122:125]
	v_mfma_f32_16x16x32_bf16 v[110:113], v[152:155], v[198:201], v[110:113]
	v_mfma_f32_16x16x32_bf16 v[110:113], v[156:159], v[216:219], v[110:113]
	v_mfma_f32_16x16x32_bf16 v[106:109], v[166:169], v[198:201], v[106:109]
	v_mfma_f32_16x16x32_bf16 v[106:109], v[170:173], v[216:219], v[106:109]
	v_mfma_f32_16x16x32_bf16 v[94:97], v[152:155], v[220:223], v[94:97]
	v_mfma_f32_16x16x32_bf16 v[94:97], v[156:159], v[224:227], v[94:97]
	v_mfma_f32_16x16x32_bf16 v[90:93], v[166:169], v[220:223], v[90:93]
	v_mfma_f32_16x16x32_bf16 v[90:93], v[170:173], v[224:227], v[90:93]
	v_mfma_f32_16x16x32_bf16 v[78:81], v[152:155], v[228:231], v[78:81]
	v_mfma_f32_16x16x32_bf16 v[78:81], v[156:159], v[232:235], v[78:81]
	v_mfma_f32_16x16x32_bf16 v[74:77], v[166:169], v[228:231], v[74:77]
	v_mfma_f32_16x16x32_bf16 v[74:77], v[170:173], v[232:235], v[74:77]
	v_mfma_f32_16x16x32_bf16 v[118:121], v[174:177], v[190:193], v[118:121]
	v_mfma_f32_16x16x32_bf16 v[118:121], v[178:181], v[194:197], v[118:121]
	v_mfma_f32_16x16x32_bf16 v[114:117], v[182:185], v[190:193], v[114:117]
	v_mfma_f32_16x16x32_bf16 v[114:117], v[186:189], v[194:197], v[114:117]
	v_mfma_f32_16x16x32_bf16 v[102:105], v[174:177], v[198:201], v[102:105]
	v_mfma_f32_16x16x32_bf16 v[102:105], v[178:181], v[216:219], v[102:105]
	v_mfma_f32_16x16x32_bf16 v[98:101], v[182:185], v[198:201], v[98:101]
	v_mfma_f32_16x16x32_bf16 v[98:101], v[186:189], v[216:219], v[98:101]
	v_mfma_f32_16x16x32_bf16 v[86:89], v[174:177], v[220:223], v[86:89]
	v_mfma_f32_16x16x32_bf16 v[86:89], v[178:181], v[224:227], v[86:89]
	v_mfma_f32_16x16x32_bf16 v[82:85], v[182:185], v[220:223], v[82:85]
	v_mfma_f32_16x16x32_bf16 v[82:85], v[186:189], v[224:227], v[82:85]
	v_mfma_f32_16x16x32_bf16 v[70:73], v[174:177], v[228:231], v[70:73]
	v_mfma_f32_16x16x32_bf16 v[70:73], v[178:181], v[232:235], v[70:73]
	v_mfma_f32_16x16x32_bf16 v[66:69], v[182:185], v[228:231], v[66:69]
	v_mfma_f32_16x16x32_bf16 v[66:69], v[186:189], v[232:235], v[66:69]
	s_barrier
	s_add_i32 s10, s12, s58
	v_lshl_add_u64 v[160:161], s[18:19], 0, v[0:1]
	s_mov_b32 m0, s10
	ds_read_b128 v[190:193], v165 offset:16384
	ds_read_b128 v[194:197], v165 offset:17408
	ds_read_b128 v[198:201], v165 offset:18432
	ds_read_b128 v[216:219], v165 offset:19456
	ds_read_b128 v[220:223], v165 offset:20480
	ds_read_b128 v[224:227], v165 offset:21504
	ds_read_b128 v[228:231], v165 offset:22528
	ds_read_b128 v[232:235], v165 offset:23552
	global_load_lds_dwordx4 v[160:161], off
	s_add_i32 m0, s10, 0x2000
	s_add_u32 s10, s18, 0x80000
	v_lshl_add_u64 v[236:237], s[18:19], 0, v[142:143]
	s_addc_u32 s11, s19, 0
	s_add_i32 s12, s13, s58
	global_load_lds_dwordx4 v[236:237], off
	v_lshl_add_u64 v[238:239], s[10:11], 0, v[0:1]
	s_mov_b32 m0, s12
	v_lshl_add_u64 v[240:241], s[24:25], 0, v[144:145]
	global_load_lds_dwordx4 v[238:239], off
	v_lshl_add_u64 v[238:239], s[10:11], 0, v[142:143]
	s_add_i32 m0, s12, 0x2000
	s_nop 0
	global_load_lds_dwordx4 v[238:239], off
	v_lshl_add_u64 v[238:239], s[24:25], 0, v[146:147]
	s_mov_b32 m0, s59
	s_nop 0
	global_load_lds_dwordx4 v[238:239], off
	s_mov_b32 m0, s60
	s_nop 0
	global_load_lds_dwordx4 v[240:241], off
	s_waitcnt vmcnt(8) lgkmcnt(0)
	s_barrier
; #define PG8_STAGE(bufoff, gbase, voff) do { _Pragma("unroll") for (int _i = 0; _i < 2; ++_i) \
;         __builtin_amdgcn_global_load_lds((const unsigned*)((const char*)(gbase) + (voff)[_i]), (PG8_LAS unsigned*)(lds + (bufoff) + ldsw + _i * 8192), 16, 0, 0); } while (0)
; #define PG8_LDA(dst, b, h) do { _Pragma("unroll") for (int m = 0; m < 4; ++m) _Pragma("unroll") for (int k = 0; k < 2; ++k) dst[m][k] = *(const PG8_LAS bf16x8*)(lds + PG8_SA(b, h) + aoff + m * 2048 + k * 1024); } while (0)
; #define PG8_LDB(dst, b, h) do { _Pragma("unroll") for (int n = 0; n < 2; ++n) _Pragma("unroll") for (int k = 0; k < 2; ++k) dst[n][k] = *(const PG8_LAS bf16x8*)(lds + PG8_SB(b, h) + boff + n * 2048 + k * 1024); } while (0)
; #define PG8_MMA(ai, bj, At, Bt) do { __builtin_amdgcn_s_setprio(1); _Pragma("unroll") for (int m = 0; m < 4; ++m) _Pragma("unroll") for (int n = 0; n < 2; ++n) _Pragma("unroll") for (int k = 0; k < 2; ++k) \
;         acc[ai][bj][m][n] = __builtin_amdgcn_mfma_f32_16x16x32_bf16(Bt[n][k], At[m][k], acc[ai][bj][m][n], 0, 0, 0); __builtin_amdgcn_s_setprio(0); } while (0)
; #define PG8_WAIT_V(n) asm volatile("s_waitcnt vmcnt(" #n ")" ::: "memory")
; #define PG8_WAIT_L(n) asm volatile("s_waitcnt lgkmcnt(" #n ")" ::: "memory")
; #define PG8_BAR __builtin_amdgcn_s_barrier()
; #define PG8_SCHED __builtin_amdgcn_sched_barrier(0)
; template <class Epi, class Sched, bool ALIGN_EPI = false, bool SP2 = false>
; __device__ __forceinline__ void gemm_phase(PG8_LAS unsigned char* lds, const Gemm g, const Sched& S, const Epi& E) {
;     ...
;             PG8_WAIT_V(8); PG8_WAIT_L(0); PG8_BAR; PG8_MMA(1, 0, At, B0); PG8_MMA(1, 1, At, B1); PG8_BAR; PG8_SCHED;
;             PG8_LDB(B0, 1, 0); PG8_LDB(B1, 1, 1); PG8_SCHED; PG8_LDA(At, 1, 0); PG8_STAGE(PG8_SA(0, 1), a2 + hstep, voffA);
;             PG8_WAIT_V(8); PG8_WAIT_L(0); PG8_BAR; PG8_MMA(0, 0, At, B0); PG8_MMA(0, 1, At, B1); PG8_BAR; PG8_SCHED;
	v_mfma_f32_16x16x32_bf16 v[62:65], v[152:155], v[190:193], v[62:65]
	v_mfma_f32_16x16x32_bf16 v[62:65], v[156:159], v[194:197], v[62:65]
	v_mfma_f32_16x16x32_bf16 v[58:61], v[166:169], v[190:193], v[58:61]
	v_mfma_f32_16x16x32_bf16 v[58:61], v[170:173], v[194:197], v[58:61]
	v_mfma_f32_16x16x32_bf16 v[46:49], v[152:155], v[198:201], v[46:49]
	v_mfma_f32_16x16x32_bf16 v[46:49], v[156:159], v[216:219], v[46:49]
	v_mfma_f32_16x16x32_bf16 v[42:45], v[166:169], v[198:201], v[42:45]
	v_mfma_f32_16x16x32_bf16 v[42:45], v[170:173], v[216:219], v[42:45]
	v_mfma_f32_16x16x32_bf16 v[30:33], v[152:155], v[220:223], v[30:33]
	v_mfma_f32_16x16x32_bf16 v[30:33], v[156:159], v[224:227], v[30:33]
	v_mfma_f32_16x16x32_bf16 v[26:29], v[166:169], v[220:223], v[26:29]
	v_mfma_f32_16x16x32_bf16 v[26:29], v[170:173], v[224:227], v[26:29]
	v_mfma_f32_16x16x32_bf16 v[14:17], v[152:155], v[228:231], v[14:17]
	v_mfma_f32_16x16x32_bf16 v[14:17], v[156:159], v[232:235], v[14:17]
	v_mfma_f32_16x16x32_bf16 v[10:13], v[166:169], v[228:231], v[10:13]
	v_mfma_f32_16x16x32_bf16 v[10:13], v[170:173], v[232:235], v[10:13]
	v_mfma_f32_16x16x32_bf16 v[54:57], v[174:177], v[190:193], v[54:57]
	v_mfma_f32_16x16x32_bf16 v[54:57], v[178:181], v[194:197], v[54:57]
	v_mfma_f32_16x16x32_bf16 v[50:53], v[182:185], v[190:193], v[50:53]
	v_mfma_f32_16x16x32_bf16 v[50:53], v[186:189], v[194:197], v[50:53]
	v_mfma_f32_16x16x32_bf16 v[38:41], v[174:177], v[198:201], v[38:41]
	v_mfma_f32_16x16x32_bf16 v[38:41], v[178:181], v[216:219], v[38:41]
	v_mfma_f32_16x16x32_bf16 v[34:37], v[182:185], v[198:201], v[34:37]
	v_mfma_f32_16x16x32_bf16 v[34:37], v[186:189], v[216:219], v[34:37]
	v_mfma_f32_16x16x32_bf16 v[22:25], v[174:177], v[220:223], v[22:25]
	v_mfma_f32_16x16x32_bf16 v[22:25], v[178:181], v[224:227], v[22:25]
	v_mfma_f32_16x16x32_bf16 v[18:21], v[182:185], v[220:223], v[18:21]
	v_mfma_f32_16x16x32_bf16 v[18:21], v[186:189], v[224:227], v[18:21]
	v_mfma_f32_16x16x32_bf16 v[6:9], v[174:177], v[228:231], v[6:9]
	v_mfma_f32_16x16x32_bf16 v[6:9], v[178:181], v[232:235], v[6:9]
	v_mfma_f32_16x16x32_bf16 v[2:5], v[182:185], v[228:231], v[2:5]
	v_mfma_f32_16x16x32_bf16 v[2:5], v[186:189], v[232:235], v[2:5]
	s_barrier
	s_add_i32 s12, 0, 0x18000
	s_add_i32 s13, 0, 0x1c000
	v_add_u32_e32 v170, s12, v163
	v_add_u32_e32 v186, s13, v163
	ds_read_b128 v[152:155], v170
	ds_read_b128 v[156:159], v170 offset:1024
	ds_read_b128 v[166:169], v170 offset:2048
	ds_read_b128 v[170:173], v170 offset:3072
	ds_read_b128 v[174:177], v186
	ds_read_b128 v[178:181], v186 offset:1024
	ds_read_b128 v[182:185], v186 offset:2048
	ds_read_b128 v[186:189], v186 offset:3072
	s_add_u32 s10, s24, 0x80000
	s_addc_u32 s11, s25, 0
	s_mov_b32 m0, s61
	v_lshl_add_u64 v[242:243], s[10:11], 0, v[146:147]
	ds_read_b128 v[190:193], v165 offset:32768
	ds_read_b128 v[194:197], v165 offset:33792
	ds_read_b128 v[198:201], v165 offset:34816
	ds_read_b128 v[216:219], v165 offset:35840
	ds_read_b128 v[220:223], v165 offset:36864
	ds_read_b128 v[224:227], v165 offset:37888
	ds_read_b128 v[228:231], v165 offset:38912
	ds_read_b128 v[232:235], v165 offset:39936
	global_load_lds_dwordx4 v[242:243], off
	v_lshl_add_u64 v[242:243], s[10:11], 0, v[144:145]
	s_mov_b32 m0, s62
	s_nop 0
	global_load_lds_dwordx4 v[242:243], off
	s_waitcnt vmcnt(8) lgkmcnt(0)
	s_barrier
	v_mfma_f32_16x16x32_bf16 v[126:129], v[152:155], v[190:193], v[126:129]
	v_mfma_f32_16x16x32_bf16 v[126:129], v[156:159], v[194:197], v[126:129]
	v_mfma_f32_16x16x32_bf16 v[122:125], v[166:169], v[190:193], v[122:125]
	v_mfma_f32_16x16x32_bf16 v[122:125], v[170:173], v[194:197], v[122:125]
	v_mfma_f32_16x16x32_bf16 v[110:113], v[152:155], v[198:201], v[110:113]
	v_mfma_f32_16x16x32_bf16 v[110:113], v[156:159], v[216:219], v[110:113]
	v_mfma_f32_16x16x32_bf16 v[106:109], v[166:169], v[198:201], v[106:109]
	v_mfma_f32_16x16x32_bf16 v[106:109], v[170:173], v[216:219], v[106:109]
	v_mfma_f32_16x16x32_bf16 v[94:97], v[152:155], v[220:223], v[94:97]
	v_mfma_f32_16x16x32_bf16 v[94:97], v[156:159], v[224:227], v[94:97]
	v_mfma_f32_16x16x32_bf16 v[90:93], v[166:169], v[220:223], v[90:93]
	v_mfma_f32_16x16x32_bf16 v[90:93], v[170:173], v[224:227], v[90:93]
	v_mfma_f32_16x16x32_bf16 v[78:81], v[152:155], v[228:231], v[78:81]
	v_mfma_f32_16x16x32_bf16 v[78:81], v[156:159], v[232:235], v[78:81]
	v_mfma_f32_16x16x32_bf16 v[74:77], v[166:169], v[228:231], v[74:77]
	v_mfma_f32_16x16x32_bf16 v[74:77], v[170:173], v[232:235], v[74:77]
	v_mfma_f32_16x16x32_bf16 v[118:121], v[174:177], v[190:193], v[118:121]
	v_mfma_f32_16x16x32_bf16 v[118:121], v[178:181], v[194:197], v[118:121]
	v_mfma_f32_16x16x32_bf16 v[114:117], v[182:185], v[190:193], v[114:117]
	v_mfma_f32_16x16x32_bf16 v[114:117], v[186:189], v[194:197], v[114:117]
	v_mfma_f32_16x16x32_bf16 v[102:105], v[174:177], v[198:201], v[102:105]
	v_mfma_f32_16x16x32_bf16 v[102:105], v[178:181], v[216:219], v[102:105]
	v_mfma_f32_16x16x32_bf16 v[98:101], v[182:185], v[198:201], v[98:101]
	v_mfma_f32_16x16x32_bf16 v[98:101], v[186:189], v[216:219], v[98:101]
	v_mfma_f32_16x16x32_bf16 v[86:89], v[174:177], v[220:223], v[86:89]
	v_mfma_f32_16x16x32_bf16 v[86:89], v[178:181], v[224:227], v[86:89]
	v_mfma_f32_16x16x32_bf16 v[82:85], v[182:185], v[220:223], v[82:85]
	v_mfma_f32_16x16x32_bf16 v[82:85], v[186:189], v[224:227], v[82:85]
	v_mfma_f32_16x16x32_bf16 v[70:73], v[174:177], v[228:231], v[70:73]
	v_mfma_f32_16x16x32_bf16 v[70:73], v[178:181], v[232:235], v[70:73]
	v_mfma_f32_16x16x32_bf16 v[66:69], v[182:185], v[228:231], v[66:69]
	v_mfma_f32_16x16x32_bf16 v[66:69], v[186:189], v[232:235], v[66:69]
	s_barrier
; #define PG8_STAGE(bufoff, gbase, voff) do { _Pragma("unroll") for (int _i = 0; _i < 2; ++_i) \
;         __builtin_amdgcn_global_load_lds((const unsigned*)((const char*)(gbase) + (voff)[_i]), (PG8_LAS unsigned*)(lds + (bufoff) + ldsw + _i * 8192), 16, 0, 0); } while (0)
; #define PG8_LDA(dst, b, h) do { _Pragma("unroll") for (int m = 0; m < 4; ++m) _Pragma("unroll") for (int k = 0; k < 2; ++k) dst[m][k] = *(const PG8_LAS bf16x8*)(lds + PG8_SA(b, h) + aoff + m * 2048 + k * 1024); } while (0)
; #define PG8_MMA(ai, bj, At, Bt) do { __builtin_amdgcn_s_setprio(1); _Pragma("unroll") for (int m = 0; m < 4; ++m) _Pragma("unroll") for (int n = 0; n < 2; ++n) _Pragma("unroll") for (int k = 0; k < 2; ++k) \
;         acc[ai][bj][m][n] = __builtin_amdgcn_mfma_f32_16x16x32_bf16(Bt[n][k], At[m][k], acc[ai][bj][m][n], 0, 0, 0); __builtin_amdgcn_s_setprio(0); } while (0)
; #define PG8_WAIT_V(n) asm volatile("s_waitcnt vmcnt(" #n ")" ::: "memory")
; #define PG8_WAIT_L(n) asm volatile("s_waitcnt lgkmcnt(" #n ")" ::: "memory")
; #define PG8_BAR __builtin_amdgcn_s_barrier()
; #define PG8_SCHED __builtin_amdgcn_sched_barrier(0)
; template <class Epi, class Sched, bool ALIGN_EPI = false, bool SP2 = false>
; __device__ __forceinline__ void gemm_phase(PG8_LAS unsigned char* lds, const Gemm g, const Sched& S, const Epi& E) {
;     ...
;         for (int t = 0; t < nt; t += 2) {
;             const bool last = (t == nt - 2);
;     ...
;             PG8_LDA(At, 1, 1); PG8_STAGE(PG8_SB(1, 0), b3, voffB); PG8_STAGE(PG8_SB(1, 1), b3 + hstep, voffB); PG8_STAGE(PG8_SA(1, 0), a3, voffA);
;             PG8_WAIT_V(8); PG8_WAIT_L(0); PG8_BAR; PG8_MMA(1, 0, At, B0); PG8_MMA(1, 1, At, B1); PG8_BAR; PG8_SCHED;
	s_add_i32 s10, s12, s58
	v_lshl_add_u64 v[160:161], v[160:161], 0, s[30:31]
	s_mov_b32 m0, s10
	ds_read_b128 v[190:193], v165 offset:49152
	ds_read_b128 v[194:197], v165 offset:50176
	ds_read_b128 v[198:201], v165 offset:51200
	ds_read_b128 v[216:219], v165 offset:52224
	ds_read_b128 v[220:223], v165 offset:53248
	ds_read_b128 v[224:227], v165 offset:54272
	ds_read_b128 v[228:231], v165 offset:55296
	ds_read_b128 v[232:235], v165 offset:56320
	global_load_lds_dwordx4 v[160:161], off
	s_add_i32 m0, s10, 0x2000
	s_add_u32 s10, s18, 0x80080
	v_lshl_add_u64 v[160:161], v[236:237], 0, s[30:31]
	s_addc_u32 s11, s19, 0
	s_add_i32 s12, s13, s58
	global_load_lds_dwordx4 v[160:161], off
	v_lshl_add_u64 v[160:161], s[10:11], 0, v[0:1]
	s_mov_b32 m0, s12
	s_nop 0
	global_load_lds_dwordx4 v[160:161], off
	v_lshl_add_u64 v[160:161], s[10:11], 0, v[142:143]
	s_add_i32 m0, s12, 0x2000
	s_nop 0
	global_load_lds_dwordx4 v[160:161], off
	v_lshl_add_u64 v[160:161], v[238:239], 0, s[30:31]
	s_mov_b32 m0, s63
	s_nop 0
	global_load_lds_dwordx4 v[160:161], off
	v_lshl_add_u64 v[160:161], v[240:241], 0, s[30:31]
	s_mov_b32 m0, s64
	s_nop 0
	global_load_lds_dwordx4 v[160:161], off
	s_waitcnt vmcnt(8) lgkmcnt(0)
	s_barrier
	v_mfma_f32_16x16x32_bf16 v[62:65], v[152:155], v[190:193], v[62:65]
	v_mfma_f32_16x16x32_bf16 v[62:65], v[156:159], v[194:197], v[62:65]
	v_mfma_f32_16x16x32_bf16 v[58:61], v[166:169], v[190:193], v[58:61]
	v_mfma_f32_16x16x32_bf16 v[58:61], v[170:173], v[194:197], v[58:61]
	v_mfma_f32_16x16x32_bf16 v[46:49], v[152:155], v[198:201], v[46:49]
	v_mfma_f32_16x16x32_bf16 v[46:49], v[156:159], v[216:219], v[46:49]
	v_mfma_f32_16x16x32_bf16 v[42:45], v[166:169], v[198:201], v[42:45]
	v_mfma_f32_16x16x32_bf16 v[42:45], v[170:173], v[216:219], v[42:45]
	v_mfma_f32_16x16x32_bf16 v[30:33], v[152:155], v[220:223], v[30:33]
	v_mfma_f32_16x16x32_bf16 v[30:33], v[156:159], v[224:227], v[30:33]
	v_mfma_f32_16x16x32_bf16 v[26:29], v[166:169], v[220:223], v[26:29]
	v_mfma_f32_16x16x32_bf16 v[26:29], v[170:173], v[224:227], v[26:29]
	v_mfma_f32_16x16x32_bf16 v[14:17], v[152:155], v[228:231], v[14:17]
	v_mfma_f32_16x16x32_bf16 v[14:17], v[156:159], v[232:235], v[14:17]
	v_mfma_f32_16x16x32_bf16 v[10:13], v[166:169], v[228:231], v[10:13]
	v_mfma_f32_16x16x32_bf16 v[10:13], v[170:173], v[232:235], v[10:13]
	v_mfma_f32_16x16x32_bf16 v[54:57], v[174:177], v[190:193], v[54:57]
	v_mfma_f32_16x16x32_bf16 v[54:57], v[178:181], v[194:197], v[54:57]
	v_mfma_f32_16x16x32_bf16 v[50:53], v[182:185], v[190:193], v[50:53]
	v_mfma_f32_16x16x32_bf16 v[50:53], v[186:189], v[194:197], v[50:53]
	v_mfma_f32_16x16x32_bf16 v[38:41], v[174:177], v[198:201], v[38:41]
	v_mfma_f32_16x16x32_bf16 v[38:41], v[178:181], v[216:219], v[38:41]
	v_mfma_f32_16x16x32_bf16 v[34:37], v[182:185], v[198:201], v[34:37]
	v_mfma_f32_16x16x32_bf16 v[34:37], v[186:189], v[216:219], v[34:37]
	v_mfma_f32_16x16x32_bf16 v[22:25], v[174:177], v[220:223], v[22:25]
	v_mfma_f32_16x16x32_bf16 v[22:25], v[178:181], v[224:227], v[22:25]
	v_mfma_f32_16x16x32_bf16 v[18:21], v[182:185], v[220:223], v[18:21]
	v_mfma_f32_16x16x32_bf16 v[18:21], v[186:189], v[224:227], v[18:21]
	v_mfma_f32_16x16x32_bf16 v[6:9], v[174:177], v[228:231], v[6:9]
	v_mfma_f32_16x16x32_bf16 v[6:9], v[178:181], v[232:235], v[6:9]
	v_mfma_f32_16x16x32_bf16 v[2:5], v[182:185], v[228:231], v[2:5]
	v_mfma_f32_16x16x32_bf16 v[2:5], v[186:189], v[232:235], v[2:5]
	s_barrier
	s_add_i32 s22, s22, 2
	s_add_u32 s16, s16, 0x100
	s_addc_u32 s17, s17, 0
	s_add_u32 s14, s14, 0x100
	s_addc_u32 s15, s15, 0
	s_cmp_gt_u32 s22, 29
	s_cbranch_scc0 .LBB0_686
	s_and_b64 vcc, exec, s[50:51]
	s_cbranch_vccz .LBB0_689
	s_barrier

; #define PG8_STAGE(bufoff, gbase, voff) do { _Pragma("unroll") for (int _i = 0; _i < 2; ++_i) \
;         __builtin_amdgcn_global_load_lds((const unsigned*)((const char*)(gbase) + (voff)[_i]), (PG8_LAS unsigned*)(lds + (bufoff) + ldsw + _i * 8192), 16, 0, 0); } while (0)
; #define PG8_LDA(dst, b, h) do { _Pragma("unroll") for (int m = 0; m < 4; ++m) _Pragma("unroll") for (int k = 0; k < 2; ++k) dst[m][k] = *(const PG8_LAS bf16x8*)(lds + PG8_SA(b, h) + aoff + m * 2048 + k * 1024); } while (0)
; #define PG8_LDB(dst, b, h) do { _Pragma("unroll") for (int n = 0; n < 2; ++n) _Pragma("unroll") for (int k = 0; k < 2; ++k) dst[n][k] = *(const PG8_LAS bf16x8*)(lds + PG8_SB(b, h) + boff + n * 2048 + k * 1024); } while (0)
; #define PG8_MMA(ai, bj, At, Bt) do { __builtin_amdgcn_s_setprio(1); _Pragma("unroll") for (int m = 0; m < 4; ++m) _Pragma("unroll") for (int n = 0; n < 2; ++n) _Pragma("unroll") for (int k = 0; k < 2; ++k) \
;         acc[ai][bj][m][n] = __builtin_amdgcn_mfma_f32_16x16x32_bf16(Bt[n][k], At[m][k], acc[ai][bj][m][n], 0, 0, 0); __builtin_amdgcn_s_setprio(0); } while (0)
; #define PG8_WAIT_V(n) asm volatile("s_waitcnt vmcnt(" #n ")" ::: "memory")
; #define PG8_WAIT_L(n) asm volatile("s_waitcnt lgkmcnt(" #n ")" ::: "memory")
; #define PG8_BAR __builtin_amdgcn_s_barrier()
; #define PG8_SCHED __builtin_amdgcn_sched_barrier(0)
; template <class Epi, class Sched, bool ALIGN_EPI = false, bool SP2 = false>
; __device__ __forceinline__ void gemm_phase(PG8_LAS unsigned char* lds, const Gemm g, const Sched& S, const Epi& E) {
;     ...
;             const bool last = (t == nt - 2);
;             const char* a1 = cA + (size_t)(t + 1) * kstep;
;             const char* a2 = last ? nA : cA + (size_t)(t + 2) * kstep; const char* b2 = last ? nB : cB + (size_t)(t + 2) * kstep;
;             const char* a3 = a2 + kstep; const char* b3 = b2 + kstep;
;             if (last && has_next) S.a_ready(nxt);
;             if constexpr (SP2) {
;             PG8_LDB(B0, 0, 0); PG8_LDB(B1, 0, 1); PG8_SCHED; PG8_LDA(At, 0, 0); PG8_STAGE(PG8_SA(1, 1), a1 + hstep, voffA);
;             PG8_WAIT_V(8); PG8_WAIT_L(0); PG8_BAR; PG8_MMA(0, 0, At, B0); PG8_MMA(0, 1, At, B1); PG8_BAR; PG8_SCHED;
;             PG8_LDA(At, 0, 1); PG8_STAGE(PG8_SB(0, 0), b2, voffB); PG8_STAGE(PG8_SB(0, 1), b2 + hstep, voffB); PG8_STAGE(PG8_SA(0, 0), a2, voffA);
.LBB0_758:
	s_add_u32 s18, s16, 0x100
	s_addc_u32 s19, s17, 0
	s_add_i32 s10, 0, 0x10000
	s_cmpk_eq_i32 s22, 0x7c
	s_cselect_b32 s27, s5, s19
	s_cselect_b32 s26, s7, s18
	s_cselect_b32 s25, s8, s15
	s_cselect_b32 s24, s9, s14
	s_add_i32 s12, 0, 0x14000
	v_add_u32_e32 v160, s10, v216
	v_add_u32_e32 v176, s12, v216
	ds_read_b128 v[148:151], v160
	ds_read_b128 v[152:155], v160 offset:1024
	ds_read_b128 v[156:159], v160 offset:2048
	ds_read_b128 v[160:163], v160 offset:3072
	ds_read_b128 v[164:167], v176
	ds_read_b128 v[168:171], v176 offset:1024
	ds_read_b128 v[172:175], v176 offset:2048
	ds_read_b128 v[176:179], v176 offset:3072
	v_lshl_add_u64 v[200:201], s[16:17], 0, v[144:145]
	s_add_i32 m0, s64, 0xc000
	ds_read_b128 v[180:183], v218
	ds_read_b128 v[184:187], v218 offset:1024
	ds_read_b128 v[188:191], v218 offset:2048
	ds_read_b128 v[192:195], v218 offset:3072
	ds_read_b128 v[196:199], v218 offset:4096
	ds_read_b128 v[220:223], v218 offset:5120
	ds_read_b128 v[224:227], v218 offset:6144
	ds_read_b128 v[228:231], v218 offset:7168
	global_load_lds_dwordx4 v[200:201], off
	v_lshl_add_u64 v[200:201], s[16:17], 0, v[146:147]
	s_add_i32 m0, s64, 0xe000
	s_nop 0
	global_load_lds_dwordx4 v[200:201], off
	s_waitcnt vmcnt(8) lgkmcnt(0)
	s_barrier
	v_mfma_f32_16x16x32_bf16 v[126:129], v[148:151], v[180:183], v[126:129]
	v_mfma_f32_16x16x32_bf16 v[126:129], v[152:155], v[184:187], v[126:129]
	v_mfma_f32_16x16x32_bf16 v[122:125], v[156:159], v[180:183], v[122:125]
	v_mfma_f32_16x16x32_bf16 v[122:125], v[160:163], v[184:187], v[122:125]
	v_mfma_f32_16x16x32_bf16 v[110:113], v[148:151], v[188:191], v[110:113]
	v_mfma_f32_16x16x32_bf16 v[110:113], v[152:155], v[192:195], v[110:113]
	v_mfma_f32_16x16x32_bf16 v[106:109], v[156:159], v[188:191], v[106:109]
	v_mfma_f32_16x16x32_bf16 v[106:109], v[160:163], v[192:195], v[106:109]
	v_mfma_f32_16x16x32_bf16 v[94:97], v[148:151], v[196:199], v[94:97]
	v_mfma_f32_16x16x32_bf16 v[94:97], v[152:155], v[220:223], v[94:97]
	v_mfma_f32_16x16x32_bf16 v[90:93], v[156:159], v[196:199], v[90:93]
	v_mfma_f32_16x16x32_bf16 v[90:93], v[160:163], v[220:223], v[90:93]
	v_mfma_f32_16x16x32_bf16 v[78:81], v[148:151], v[224:227], v[78:81]
	v_mfma_f32_16x16x32_bf16 v[78:81], v[152:155], v[228:231], v[78:81]
	v_mfma_f32_16x16x32_bf16 v[74:77], v[156:159], v[224:227], v[74:77]
	v_mfma_f32_16x16x32_bf16 v[74:77], v[160:163], v[228:231], v[74:77]
	v_mfma_f32_16x16x32_bf16 v[118:121], v[164:167], v[180:183], v[118:121]
	v_mfma_f32_16x16x32_bf16 v[118:121], v[168:171], v[184:187], v[118:121]
	v_mfma_f32_16x16x32_bf16 v[114:117], v[172:175], v[180:183], v[114:117]
	v_mfma_f32_16x16x32_bf16 v[114:117], v[176:179], v[184:187], v[114:117]
	v_mfma_f32_16x16x32_bf16 v[102:105], v[164:167], v[188:191], v[102:105]
	v_mfma_f32_16x16x32_bf16 v[102:105], v[168:171], v[192:195], v[102:105]
	v_mfma_f32_16x16x32_bf16 v[98:101], v[172:175], v[188:191], v[98:101]
	v_mfma_f32_16x16x32_bf16 v[98:101], v[176:179], v[192:195], v[98:101]
	v_mfma_f32_16x16x32_bf16 v[86:89], v[164:167], v[196:199], v[86:89]
	v_mfma_f32_16x16x32_bf16 v[86:89], v[168:171], v[220:223], v[86:89]
	v_mfma_f32_16x16x32_bf16 v[82:85], v[172:175], v[196:199], v[82:85]
	v_mfma_f32_16x16x32_bf16 v[82:85], v[176:179], v[220:223], v[82:85]
	v_mfma_f32_16x16x32_bf16 v[70:73], v[164:167], v[224:227], v[70:73]
	v_mfma_f32_16x16x32_bf16 v[70:73], v[168:171], v[228:231], v[70:73]
	v_mfma_f32_16x16x32_bf16 v[66:69], v[172:175], v[224:227], v[66:69]
	v_mfma_f32_16x16x32_bf16 v[66:69], v[176:179], v[228:231], v[66:69]
	s_barrier
	s_add_i32 s10, s10, s63
	v_lshl_add_u64 v[200:201], s[24:25], 0, v[0:1]
	s_mov_b32 m0, s10
	ds_read_b128 v[180:183], v218 offset:16384
	ds_read_b128 v[184:187], v218 offset:17408
	ds_read_b128 v[188:191], v218 offset:18432
	ds_read_b128 v[192:195], v218 offset:19456
	ds_read_b128 v[196:199], v218 offset:20480
	ds_read_b128 v[220:223], v218 offset:21504
	ds_read_b128 v[224:227], v218 offset:22528
	ds_read_b128 v[228:231], v218 offset:23552
	global_load_lds_dwordx4 v[200:201], off
	s_add_i32 m0, s10, 0x2000
	s_add_u32 s10, s24, 0x200000
	v_lshl_add_u64 v[232:233], s[24:25], 0, v[142:143]
	s_addc_u32 s11, s25, 0
	s_add_i32 s12, s12, s63
	global_load_lds_dwordx4 v[232:233], off
	v_lshl_add_u64 v[234:235], s[10:11], 0, v[0:1]
	s_mov_b32 m0, s12
	v_lshl_add_u64 v[236:237], s[26:27], 0, v[142:143]
	global_load_lds_dwordx4 v[234:235], off
	v_lshl_add_u64 v[234:235], s[10:11], 0, v[142:143]
	s_add_i32 m0, s12, 0x2000
	s_nop 0
	global_load_lds_dwordx4 v[234:235], off
	v_lshl_add_u64 v[234:235], s[26:27], 0, v[0:1]
	s_mov_b32 m0, s64
	s_nop 0
	global_load_lds_dwordx4 v[234:235], off
	s_mov_b32 m0, s65
	s_nop 0
	global_load_lds_dwordx4 v[236:237], off
	s_waitcnt vmcnt(8) lgkmcnt(0)
	s_barrier
; #define PG8_STAGE(bufoff, gbase, voff) do { _Pragma("unroll") for (int _i = 0; _i < 2; ++_i) \
;         __builtin_amdgcn_global_load_lds((const unsigned*)((const char*)(gbase) + (voff)[_i]), (PG8_LAS unsigned*)(lds + (bufoff) + ldsw + _i * 8192), 16, 0, 0); } while (0)
; #define PG8_LDA(dst, b, h) do { _Pragma("unroll") for (int m = 0; m < 4; ++m) _Pragma("unroll") for (int k = 0; k < 2; ++k) dst[m][k] = *(const PG8_LAS bf16x8*)(lds + PG8_SA(b, h) + aoff + m * 2048 + k * 1024); } while (0)
; #define PG8_LDB(dst, b, h) do { _Pragma("unroll") for (int n = 0; n < 2; ++n) _Pragma("unroll") for (int k = 0; k < 2; ++k) dst[n][k] = *(const PG8_LAS bf16x8*)(lds + PG8_SB(b, h) + boff + n * 2048 + k * 1024); } while (0)
; #define PG8_MMA(ai, bj, At, Bt) do { __builtin_amdgcn_s_setprio(1); _Pragma("unroll") for (int m = 0; m < 4; ++m) _Pragma("unroll") for (int n = 0; n < 2; ++n) _Pragma("unroll") for (int k = 0; k < 2; ++k) \
;         acc[ai][bj][m][n] = __builtin_amdgcn_mfma_f32_16x16x32_bf16(Bt[n][k], At[m][k], acc[ai][bj][m][n], 0, 0, 0); __builtin_amdgcn_s_setprio(0); } while (0)
; #define PG8_WAIT_V(n) asm volatile("s_waitcnt vmcnt(" #n ")" ::: "memory")
; #define PG8_WAIT_L(n) asm volatile("s_waitcnt lgkmcnt(" #n ")" ::: "memory")
; #define PG8_BAR __builtin_amdgcn_s_barrier()
; #define PG8_SCHED __builtin_amdgcn_sched_barrier(0)
; template <class Epi, class Sched, bool ALIGN_EPI = false, bool SP2 = false>
; __device__ __forceinline__ void gemm_phase(PG8_LAS unsigned char* lds, const Gemm g, const Sched& S, const Epi& E) {
;     ...
;             PG8_WAIT_V(8); PG8_WAIT_L(0); PG8_BAR; PG8_MMA(1, 0, At, B0); PG8_MMA(1, 1, At, B1); PG8_BAR; PG8_SCHED;
;             PG8_LDB(B0, 1, 0); PG8_LDB(B1, 1, 1); PG8_SCHED; PG8_LDA(At, 1, 0); PG8_STAGE(PG8_SA(0, 1), a2 + hstep, voffA);
;             PG8_WAIT_V(8); PG8_WAIT_L(0); PG8_BAR; PG8_MMA(0, 0, At, B0); PG8_MMA(0, 1, At, B1); PG8_BAR; PG8_SCHED;
	v_mfma_f32_16x16x32_bf16 v[62:65], v[148:151], v[180:183], v[62:65]
	v_mfma_f32_16x16x32_bf16 v[62:65], v[152:155], v[184:187], v[62:65]
	v_mfma_f32_16x16x32_bf16 v[58:61], v[156:159], v[180:183], v[58:61]
	v_mfma_f32_16x16x32_bf16 v[58:61], v[160:163], v[184:187], v[58:61]
	v_mfma_f32_16x16x32_bf16 v[46:49], v[148:151], v[188:191], v[46:49]
	v_mfma_f32_16x16x32_bf16 v[46:49], v[152:155], v[192:195], v[46:49]
	v_mfma_f32_16x16x32_bf16 v[42:45], v[156:159], v[188:191], v[42:45]
	v_mfma_f32_16x16x32_bf16 v[42:45], v[160:163], v[192:195], v[42:45]
	v_mfma_f32_16x16x32_bf16 v[30:33], v[148:151], v[196:199], v[30:33]
	v_mfma_f32_16x16x32_bf16 v[30:33], v[152:155], v[220:223], v[30:33]
	v_mfma_f32_16x16x32_bf16 v[26:29], v[156:159], v[196:199], v[26:29]
	v_mfma_f32_16x16x32_bf16 v[26:29], v[160:163], v[220:223], v[26:29]
	v_mfma_f32_16x16x32_bf16 v[14:17], v[148:151], v[224:227], v[14:17]
	v_mfma_f32_16x16x32_bf16 v[14:17], v[152:155], v[228:231], v[14:17]
	v_mfma_f32_16x16x32_bf16 v[10:13], v[156:159], v[224:227], v[10:13]
	v_mfma_f32_16x16x32_bf16 v[10:13], v[160:163], v[228:231], v[10:13]
	v_mfma_f32_16x16x32_bf16 v[54:57], v[164:167], v[180:183], v[54:57]
	v_mfma_f32_16x16x32_bf16 v[54:57], v[168:171], v[184:187], v[54:57]
	v_mfma_f32_16x16x32_bf16 v[50:53], v[172:175], v[180:183], v[50:53]
	v_mfma_f32_16x16x32_bf16 v[50:53], v[176:179], v[184:187], v[50:53]
	v_mfma_f32_16x16x32_bf16 v[38:41], v[164:167], v[188:191], v[38:41]
	v_mfma_f32_16x16x32_bf16 v[38:41], v[168:171], v[192:195], v[38:41]
	v_mfma_f32_16x16x32_bf16 v[34:37], v[172:175], v[188:191], v[34:37]
	v_mfma_f32_16x16x32_bf16 v[34:37], v[176:179], v[192:195], v[34:37]
	v_mfma_f32_16x16x32_bf16 v[22:25], v[164:167], v[196:199], v[22:25]
	v_mfma_f32_16x16x32_bf16 v[22:25], v[168:171], v[220:223], v[22:25]
	v_mfma_f32_16x16x32_bf16 v[18:21], v[172:175], v[196:199], v[18:21]
	v_mfma_f32_16x16x32_bf16 v[18:21], v[176:179], v[220:223], v[18:21]
	v_mfma_f32_16x16x32_bf16 v[6:9], v[164:167], v[224:227], v[6:9]
	v_mfma_f32_16x16x32_bf16 v[6:9], v[168:171], v[228:231], v[6:9]
	v_mfma_f32_16x16x32_bf16 v[2:5], v[172:175], v[224:227], v[2:5]
	v_mfma_f32_16x16x32_bf16 v[2:5], v[176:179], v[228:231], v[2:5]
	s_barrier
	s_add_i32 s12, 0, 0x18000
	s_add_i32 s13, 0, 0x1c000
	v_add_u32_e32 v160, s12, v216
	v_add_u32_e32 v176, s13, v216
	ds_read_b128 v[148:151], v160
	ds_read_b128 v[152:155], v160 offset:1024
	ds_read_b128 v[156:159], v160 offset:2048
	ds_read_b128 v[160:163], v160 offset:3072
	ds_read_b128 v[164:167], v176
	ds_read_b128 v[168:171], v176 offset:1024
	ds_read_b128 v[172:175], v176 offset:2048
	ds_read_b128 v[176:179], v176 offset:3072
	s_add_u32 s10, s26, 0x200000
	s_addc_u32 s11, s27, 0
	s_mov_b32 m0, s66
	v_lshl_add_u64 v[238:239], s[10:11], 0, v[0:1]
	ds_read_b128 v[180:183], v218 offset:32768
	ds_read_b128 v[184:187], v218 offset:33792
	ds_read_b128 v[188:191], v218 offset:34816
	ds_read_b128 v[192:195], v218 offset:35840
	ds_read_b128 v[196:199], v218 offset:36864
	ds_read_b128 v[220:223], v218 offset:37888
	ds_read_b128 v[224:227], v218 offset:38912
	ds_read_b128 v[228:231], v218 offset:39936
	global_load_lds_dwordx4 v[238:239], off
	v_lshl_add_u64 v[238:239], s[10:11], 0, v[142:143]
	s_mov_b32 m0, s67
	s_nop 0
	global_load_lds_dwordx4 v[238:239], off
	s_waitcnt vmcnt(8) lgkmcnt(0)
	s_barrier
	v_mfma_f32_16x16x32_bf16 v[126:129], v[148:151], v[180:183], v[126:129]
	v_mfma_f32_16x16x32_bf16 v[126:129], v[152:155], v[184:187], v[126:129]
	v_mfma_f32_16x16x32_bf16 v[122:125], v[156:159], v[180:183], v[122:125]
	v_mfma_f32_16x16x32_bf16 v[122:125], v[160:163], v[184:187], v[122:125]
	v_mfma_f32_16x16x32_bf16 v[110:113], v[148:151], v[188:191], v[110:113]
	v_mfma_f32_16x16x32_bf16 v[110:113], v[152:155], v[192:195], v[110:113]
	v_mfma_f32_16x16x32_bf16 v[106:109], v[156:159], v[188:191], v[106:109]
	v_mfma_f32_16x16x32_bf16 v[106:109], v[160:163], v[192:195], v[106:109]
	v_mfma_f32_16x16x32_bf16 v[94:97], v[148:151], v[196:199], v[94:97]
	v_mfma_f32_16x16x32_bf16 v[94:97], v[152:155], v[220:223], v[94:97]
	v_mfma_f32_16x16x32_bf16 v[90:93], v[156:159], v[196:199], v[90:93]
	v_mfma_f32_16x16x32_bf16 v[90:93], v[160:163], v[220:223], v[90:93]
	v_mfma_f32_16x16x32_bf16 v[78:81], v[148:151], v[224:227], v[78:81]
	v_mfma_f32_16x16x32_bf16 v[78:81], v[152:155], v[228:231], v[78:81]
	v_mfma_f32_16x16x32_bf16 v[74:77], v[156:159], v[224:227], v[74:77]
	v_mfma_f32_16x16x32_bf16 v[74:77], v[160:163], v[228:231], v[74:77]
	v_mfma_f32_16x16x32_bf16 v[118:121], v[164:167], v[180:183], v[118:121]
	v_mfma_f32_16x16x32_bf16 v[118:121], v[168:171], v[184:187], v[118:121]
	v_mfma_f32_16x16x32_bf16 v[114:117], v[172:175], v[180:183], v[114:117]
	v_mfma_f32_16x16x32_bf16 v[114:117], v[176:179], v[184:187], v[114:117]
	v_mfma_f32_16x16x32_bf16 v[102:105], v[164:167], v[188:191], v[102:105]
	v_mfma_f32_16x16x32_bf16 v[102:105], v[168:171], v[192:195], v[102:105]
	v_mfma_f32_16x16x32_bf16 v[98:101], v[172:175], v[188:191], v[98:101]
	v_mfma_f32_16x16x32_bf16 v[98:101], v[176:179], v[192:195], v[98:101]
	v_mfma_f32_16x16x32_bf16 v[86:89], v[164:167], v[196:199], v[86:89]
	v_mfma_f32_16x16x32_bf16 v[86:89], v[168:171], v[220:223], v[86:89]
	v_mfma_f32_16x16x32_bf16 v[82:85], v[172:175], v[196:199], v[82:85]
	v_mfma_f32_16x16x32_bf16 v[82:85], v[176:179], v[220:223], v[82:85]
	v_mfma_f32_16x16x32_bf16 v[70:73], v[164:167], v[224:227], v[70:73]
	v_mfma_f32_16x16x32_bf16 v[70:73], v[168:171], v[228:231], v[70:73]
	v_mfma_f32_16x16x32_bf16 v[66:69], v[172:175], v[224:227], v[66:69]
	v_mfma_f32_16x16x32_bf16 v[66:69], v[176:179], v[228:231], v[66:69]
	s_barrier
; #define PG8_STAGE(bufoff, gbase, voff) do { _Pragma("unroll") for (int _i = 0; _i < 2; ++_i) \
;         __builtin_amdgcn_global_load_lds((const unsigned*)((const char*)(gbase) + (voff)[_i]), (PG8_LAS unsigned*)(lds + (bufoff) + ldsw + _i * 8192), 16, 0, 0); } while (0)
; #define PG8_WAIT_V(n) asm volatile("s_waitcnt vmcnt(" #n ")" ::: "memory")
; #define PG8_BAR __builtin_amdgcn_s_barrier()
;     __device__ __forceinline__ void operator()(const f32x4 (&acc)[2][2][4][2], const Unit& u, int wr, int wc, int fr, int fq) const {
;         const int row0 = u.pm * BM + wr * 64 + fr; const int col0 = u.pn * BM + wc * 32 + 4 * fq;
; #pragma unroll
;         for (int ai = 0; ai < 2; ++ai) {
;             u32x2 bv[4][2][2];
; #pragma unroll
;             for (int m = 0; m < 4; ++m) { const size_t off = (size_t)(row0 + ai * HALF + m * 16) * ldc + col0;
; #pragma unroll
;                 for (int bj = 0; bj < 2; ++bj)
; #pragma unroll
;                     for (int n = 0; n < 2; ++n) bv[m][bj][n] = *(const u32x2*)(xb + off + bj * HALF + n * 16); }
;             asm volatile("" ::: "memory");
; #pragma unroll
;             for (int m = 0; m < 4; ++m) {
;                 const int row = row0 + ai * HALF + m * 16;
;                 const size_t off = (size_t)row * ldc + col0;
;                 float s = 0.f;
; #pragma unroll
;                 for (int bj = 0; bj < 2; ++bj)
; #pragma unroll
;                     for (int n = 0; n < 2; ++n) {
;                         const size_t c = off + bj * HALF + n * 16;
;                         const u32x2 w0 = bv[m][bj][n];
;                         const f32x4 b = {__uint_as_float(w0.x << 16), __uint_as_float(w0.x & 0xffff0000u), __uint_as_float(w0.y << 16), __uint_as_float(w0.y & 0xffff0000u)};
;                         const f32x4 o = b + acc[ai][bj][m][n];
;                         if (fin) { *(f32x4*)(outf + c) = o; }
; template <class Epi, class Sched, bool ALIGN_EPI = false, bool SP2 = false>
; __device__ __forceinline__ void gemm_phase(PG8_LAS unsigned char* lds, const Gemm g, const Sched& S, const Epi& E) {
;     ...
;         for (int t = 0; t < nt; t += 2) {
;     ...
;             PG8_LDA(At, 1, 1); PG8_STAGE(PG8_SB(1, 0), b3, voffB); PG8_STAGE(PG8_SB(1, 1), b3 + hstep, voffB); PG8_STAGE(PG8_SA(1, 0), a3, voffA);
;             PG8_WAIT_V(8); PG8_WAIT_L(0); PG8_BAR; PG8_MMA(1, 0, At, B0); PG8_MMA(1, 1, At, B1); PG8_BAR; PG8_SCHED;
	s_add_i32 s10, s12, s63
	v_lshl_add_u64 v[200:201], v[200:201], 0, s[30:31]
	s_mov_b32 m0, s10
	ds_read_b128 v[180:183], v218 offset:49152
	ds_read_b128 v[184:187], v218 offset:50176
	ds_read_b128 v[188:191], v218 offset:51200
	ds_read_b128 v[192:195], v218 offset:52224
	ds_read_b128 v[196:199], v218 offset:53248
	ds_read_b128 v[220:223], v218 offset:54272
	ds_read_b128 v[224:227], v218 offset:55296
	ds_read_b128 v[228:231], v218 offset:56320
	global_load_lds_dwordx4 v[200:201], off
	s_add_i32 m0, s10, 0x2000
	s_add_u32 s10, s24, 0x200080
	v_lshl_add_u64 v[200:201], v[232:233], 0, s[30:31]
	s_addc_u32 s11, s25, 0
	s_add_i32 s12, s13, s63
	global_load_lds_dwordx4 v[200:201], off
	v_lshl_add_u64 v[200:201], s[10:11], 0, v[0:1]
	s_mov_b32 m0, s12
	s_nop 0
	global_load_lds_dwordx4 v[200:201], off
	v_lshl_add_u64 v[200:201], s[10:11], 0, v[142:143]
	s_add_i32 m0, s12, 0x2000
	s_nop 0
	global_load_lds_dwordx4 v[200:201], off
	v_lshl_add_u64 v[200:201], v[234:235], 0, s[30:31]
	s_mov_b32 m0, s68
	s_nop 0
	global_load_lds_dwordx4 v[200:201], off
	v_lshl_add_u64 v[200:201], v[236:237], 0, s[30:31]
	s_mov_b32 m0, s69
	s_nop 0
	global_load_lds_dwordx4 v[200:201], off
	s_waitcnt vmcnt(8) lgkmcnt(0)
	s_barrier
	v_mfma_f32_16x16x32_bf16 v[62:65], v[148:151], v[180:183], v[62:65]
	v_mfma_f32_16x16x32_bf16 v[62:65], v[152:155], v[184:187], v[62:65]
	v_mfma_f32_16x16x32_bf16 v[58:61], v[156:159], v[180:183], v[58:61]
	v_mfma_f32_16x16x32_bf16 v[58:61], v[160:163], v[184:187], v[58:61]
	v_mfma_f32_16x16x32_bf16 v[46:49], v[148:151], v[188:191], v[46:49]
	v_mfma_f32_16x16x32_bf16 v[46:49], v[152:155], v[192:195], v[46:49]
	v_mfma_f32_16x16x32_bf16 v[42:45], v[156:159], v[188:191], v[42:45]
	v_mfma_f32_16x16x32_bf16 v[42:45], v[160:163], v[192:195], v[42:45]
	v_mfma_f32_16x16x32_bf16 v[30:33], v[148:151], v[196:199], v[30:33]
	v_mfma_f32_16x16x32_bf16 v[30:33], v[152:155], v[220:223], v[30:33]
	v_mfma_f32_16x16x32_bf16 v[26:29], v[156:159], v[196:199], v[26:29]
	v_mfma_f32_16x16x32_bf16 v[26:29], v[160:163], v[220:223], v[26:29]
	v_mfma_f32_16x16x32_bf16 v[14:17], v[148:151], v[224:227], v[14:17]
	v_mfma_f32_16x16x32_bf16 v[14:17], v[152:155], v[228:231], v[14:17]
	v_mfma_f32_16x16x32_bf16 v[10:13], v[156:159], v[224:227], v[10:13]
	v_mfma_f32_16x16x32_bf16 v[10:13], v[160:163], v[228:231], v[10:13]
	v_mfma_f32_16x16x32_bf16 v[54:57], v[164:167], v[180:183], v[54:57]
	v_mfma_f32_16x16x32_bf16 v[54:57], v[168:171], v[184:187], v[54:57]
	v_mfma_f32_16x16x32_bf16 v[50:53], v[172:175], v[180:183], v[50:53]
	v_mfma_f32_16x16x32_bf16 v[50:53], v[176:179], v[184:187], v[50:53]
	v_mfma_f32_16x16x32_bf16 v[38:41], v[164:167], v[188:191], v[38:41]
	v_mfma_f32_16x16x32_bf16 v[38:41], v[168:171], v[192:195], v[38:41]
	v_mfma_f32_16x16x32_bf16 v[34:37], v[172:175], v[188:191], v[34:37]
	v_mfma_f32_16x16x32_bf16 v[34:37], v[176:179], v[192:195], v[34:37]
	v_mfma_f32_16x16x32_bf16 v[22:25], v[164:167], v[196:199], v[22:25]
	v_mfma_f32_16x16x32_bf16 v[22:25], v[168:171], v[220:223], v[22:25]
	v_mfma_f32_16x16x32_bf16 v[18:21], v[172:175], v[196:199], v[18:21]
	v_mfma_f32_16x16x32_bf16 v[18:21], v[176:179], v[220:223], v[18:21]
	v_mfma_f32_16x16x32_bf16 v[6:9], v[164:167], v[224:227], v[6:9]
	v_mfma_f32_16x16x32_bf16 v[6:9], v[168:171], v[228:231], v[6:9]
	v_mfma_f32_16x16x32_bf16 v[2:5], v[172:175], v[224:227], v[2:5]
	v_mfma_f32_16x16x32_bf16 v[2:5], v[176:179], v[228:231], v[2:5]
	s_barrier
	s_add_i32 s22, s22, 2
	s_add_u32 s14, s14, 0x100
	s_addc_u32 s15, s15, 0
	s_cmpk_gt_u32 s22, 0x7d
	s_mov_b64 s[16:17], s[18:19]
	s_cbranch_scc0 .LBB0_758
	v_lshl_add_u32 v152, s4, 8, v215
	v_lshl_or_b32 v148, s2, 8, v217
	v_ashrrev_i32_e32 v149, 31, v148
	v_ashrrev_i32_e32 v153, 31, v152
	v_or_b32_e32 v176, 16, v152
	v_lshl_add_u64 v[150:151], v[148:149], 1, s[50:51]
	v_lshlrev_b64 v[154:155], 12, v[152:153]
	v_ashrrev_i32_e32 v177, 31, v176
	v_or_b32_e32 v164, 32, v152
	v_lshl_add_u64 v[198:199], v[150:151], 0, v[154:155]
	v_lshlrev_b64 v[154:155], 12, v[176:177]
	v_ashrrev_i32_e32 v165, 31, v164
	v_lshl_add_u64 v[186:187], v[150:151], 0, v[154:155]
	v_lshlrev_b64 v[154:155], 12, v[164:165]
	v_lshl_add_u64 v[174:175], v[150:151], 0, v[154:155]
	v_or_b32_e32 v154, 48, v152
	v_ashrrev_i32_e32 v155, 31, v154
	v_lshlrev_b64 v[156:157], 12, v[154:155]
	v_lshl_add_u64 v[162:163], v[150:151], 0, v[156:157]
	global_load_dwordx2 v[192:193], v[198:199], off
	global_load_dwordx2 v[196:197], v[198:199], off offset:32
	global_load_dwordx2 v[194:195], v[198:199], off offset:256
	global_load_dwordx2 v[190:191], v[198:199], off offset:288
	global_load_dwordx2 v[188:189], v[186:187], off
	global_load_dwordx2 v[184:185], v[186:187], off offset:32
	global_load_dwordx2 v[182:183], v[186:187], off offset:256
	global_load_dwordx2 v[180:181], v[186:187], off offset:288
	global_load_dwordx2 v[178:179], v[174:175], off
	global_load_dwordx2 v[172:173], v[174:175], off offset:32
	global_load_dwordx2 v[170:171], v[174:175], off offset:256
	global_load_dwordx2 v[168:169], v[174:175], off offset:288
	global_load_dwordx2 v[166:167], v[162:163], off
	global_load_dwordx2 v[160:161], v[162:163], off offset:32
	global_load_dwordx2 v[158:159], v[162:163], off offset:256
	global_load_dwordx2 v[156:157], v[162:163], off offset:288
	v_readlane_b32 s4, v244, 52
	v_readlane_b32 s5, v244, 53
	s_mov_b64 s[16:17], -1
	s_andn2_b64 vcc, exec, s[4:5]
	v_cndmask_b32_e64 v200, 0, 1, s[4:5]
	v_cmp_ne_u32_e64 s[44:45], 1, v200
	v_lshlrev_b64 v[200:201], 11, v[152:153]
	v_lshl_add_u64 v[200:201], v[200:201], 0, v[148:149]
	s_waitcnt vmcnt(0)
	v_lshlrev_b32_e32 v220, 16, v192
	v_and_b32_e32 v221, 0xffff0000, v192
	v_lshlrev_b32_e32 v192, 16, v193
	v_and_b32_e32 v193, 0xffff0000, v193
	v_pk_add_f32 v[128:129], v[128:129], v[192:193]
	v_pk_add_f32 v[126:127], v[126:127], v[220:221]
	v_lshl_add_u64 v[192:193], v[200:201], 2, s[48:49]
	s_cbranch_vccnz .LBB0_761
	s_mov_b64 s[16:17], 0
	global_store_dwordx4 v[192:193], v[126:129], off
